# v17: K tile LDS swizzle extended with row bit 4 (conflict-free ds_read_b128 K fragments): DMA source offsets of waves 4-7 and reader addresses adjusted
# speedup vs baseline: 1.0137x; 1.0137x over previous
; __device__ __forceinline__ int v_rd_base(int lane) { return ((lane & 3) << 3) | (((lane >> 2) & 3) << 6) | (((lane >> 4) & 1) << 5) | (((lane >> 5) & 1) << 8); }
; #define RAWBAR() do { asm volatile("s_waitcnt lgkmcnt(0)" ::: "memory"); __builtin_amdgcn_s_barrier(); asm volatile("" ::: "memory"); } while (0)
; #define RAWBAR() do { asm volatile("s_waitcnt lgkmcnt(0)" ::: "memory"); __builtin_amdgcn_s_barrier(); asm volatile("" ::: "memory"); } while (0)
; #define RAWBAR() do { asm volatile("s_waitcnt lgkmcnt(0)" ::: "memory"); __builtin_amdgcn_s_barrier(); asm volatile("" ::: "memory"); } while (0)
; #define RAWBAR() do { asm volatile("s_waitcnt lgkmcnt(0)" ::: "memory"); __builtin_amdgcn_s_barrier(); asm volatile("" ::: "memory"); } while (0)
; #define RAWBAR() do { asm volatile("s_waitcnt lgkmcnt(0)" ::: "memory"); __builtin_amdgcn_s_barrier(); asm volatile("" ::: "memory"); } while (0)
; #define RAWBAR() do { asm volatile("s_waitcnt lgkmcnt(0)" ::: "memory"); __builtin_amdgcn_s_barrier(); asm volatile("" ::: "memory"); } while (0)
; template <int MODE> ...
;     ...
;   const bf16* Qw = Qb + (long)(g * 32 + r32) * 128 + hi * 8;
; #pragma unroll
;   for (int d0 = 0; d0 < 8; ++d0) qr[d0] = St::ld8(Qw + d0 * 16);
;   const int vb0 = (int)(uintptr_t)V_lds + v_rd_base(lane) + 2 * kh * 4096;
;   const int krow = 32 * kh + r32;
;   typedef __attribute__((address_space(3))) unsigned lds_u32;
;   const int wu = __builtin_amdgcn_readfirstlane(wid);
;   long gk[2], gv[2];
; #pragma unroll
;   for (int c = 0; c < 2; ++c) { const int q = wu + 8 * c;
;     const int r = 4 * q + (lane >> 4), pch = lane & 15; gk[c] = (long)r * 128 + ((pch ^ (r & 7)) * 8);
;     const int st = 2 * q + (lane >> 5), kk = (st >> 2) * 8 + ((lane >> 2) & 7), k = (kk & ~0xC) | ((kk & 4) << 1) | ((kk & 8) >> 1), cc = (st & 3) * 32 + (lane & 3) * 8;
;     gv[c] = (long)k * 256 + cc; }
;     ...
;   const int NT = seq / KVBLK;
;   STAGE(0, 0); asm volatile("s_waitcnt vmcnt(0)" ::: "memory"); RAWBAR();
.LBB0_1017:
	s_mov_b64 s[24:25], -1
	s_and_b64 vcc, exec, s[22:23]
	s_cbranch_vccz .LBB0_1010
	s_ashr_i32 s29, s28, 31
	s_mul_i32 s2, s40, 0x8200
	s_lshl_b64 s[22:23], s[28:29], 7
	v_mov_b32_e32 v197, v224
	s_mul_hi_i32 s3, s40, 0x8200
	s_add_u32 s2, s2, s22
	s_addc_u32 s3, s3, s23
	v_ashrrev_i32_e32 v213, 7, v197
	v_and_b32_e32 v206, 31, v197
	v_lshlrev_b32_e32 v196, 5, v213
	s_lshl_b64 s[2:3], s[2:3], 8
	v_or_b32_e32 v0, v196, v206
	s_add_u32 s34, s52, s2
	v_ashrrev_i32_e32 v1, 31, v0
	s_addc_u32 s35, s53, s3
	s_mul_i32 s26, s40, 0x820000
	v_bfe_u32 v207, v197, 5, 1
	v_lshlrev_b64 v[0:1], 8, v[0:1]
	s_mul_hi_i32 s27, s40, 0x820000
	s_add_u32 s36, s47, s26
	v_lshl_add_u64 v[0:1], s[34:35], 0, v[0:1]
	v_lshlrev_b32_e32 v194, 4, v207
	s_addc_u32 s37, s48, s27
	v_lshl_add_u64 v[0:1], v[0:1], 0, v[194:195]
	v_ashrrev_i32_e32 v8, 6, v197
	s_add_u32 s30, s49, s26
	global_load_dwordx4 v[188:191], v[0:1], off
	global_load_dwordx4 v[184:187], v[0:1], off offset:32
	global_load_dwordx4 v[180:183], v[0:1], off offset:64
	global_load_dwordx4 v[176:179], v[0:1], off offset:96
	global_load_dwordx4 v[172:175], v[0:1], off offset:128
	global_load_dwordx4 v[168:171], v[0:1], off offset:160
	global_load_dwordx4 v[164:167], v[0:1], off offset:192
	global_load_dwordx4 v[160:163], v[0:1], off offset:224
	v_readfirstlane_b32 s2, v8
	v_bfe_u32 v0, v197, 2, 2
	v_lshrrev_b32_e32 v1, 1, v197
	s_addc_u32 s31, s50, s27
	v_bfe_u32 v4, v197, 4, 2
	v_and_or_b32 v7, v1, 8, v0
	v_lshlrev_b32_e32 v0, 3, v197
	s_lshl_b32 s3, s2, 2
	s_lshl_b32 s24, s2, 1
	v_and_b32_e32 v13, 24, v0
	v_or_b32_e32 v0, s3, v4
	s_and_b32 s3, s3, -16
	s_and_b32 s25, s24, 4
	v_and_b32_e32 v2, 63, v197
	s_or_b32 s3, s3, s25
	v_lshlrev_b32_e32 v9, 3, v2
	v_lshlrev_b32_e32 v212, 4, v2
	v_or_b32_e32 v2, s3, v7
	s_add_i32 s3, s2, 8
	v_and_or_b32 v14, s24, 2, v207
	s_lshl_b32 s24, s3, 2
	s_lshl_b32 s25, s3, 1
	v_or_b32_e32 v4, s24, v4
	s_and_b32 s24, s24, -16
	s_and_b32 s33, s25, 4
	v_and_b32_e32 v6, 15, v197
	v_ashrrev_i32_e32 v1, 31, v0
	s_or_b32 s24, s24, s33
	v_and_b32_e32 v12, 0x100, v9
	v_bitop3_b32 v11, v0, v6, 7 bitop3:0x6c
	v_ashrrev_i32_e32 v5, 31, v4
	v_bitop3_b32 v15, v4, v6, 7 bitop3:0x6c
	v_or_b32_e32 v6, s24, v7
	v_and_b32_e32 v211, 1, v8
	v_and_b32_e32 v17, 24, v9
	v_lshlrev_b64 v[8:9], 8, v[0:1]
	s_lshl_b32 s24, s2, 10
	v_lshlrev_b32_e32 v10, 1, v197
	v_and_or_b32 v16, s25, 2, v207
	v_lshl_or_b32 v8, v11, 4, v8
	s_add_i32 s25, s24, 0
	v_lshlrev_b64 v[4:5], 8, v[4:5]
	v_lshlrev_b32_e32 v15, 4, v15
	v_lshrrev_b32_e32 v132, 1, v197
	v_and_b32_e32 v132, 0x80, v132
	v_xor_b32_e32 v8, v8, v132
	v_xor_b32_e32 v15, v15, v132
	v_ashrrev_i32_e32 v3, 31, v2
	v_and_b32_e32 v19, 32, v10
	v_lshl_add_u64 v[10:11], s[36:37], 0, v[8:9]
	s_mov_b32 m0, s25
	v_or_b32_e32 v4, v4, v15
	v_ashrrev_i32_e32 v7, 31, v6
	global_load_lds_dwordx4 v[10:11], off
	v_lshl_add_u64 v[128:129], v[10:11], 0, s[18:19]
	v_lshl_add_u64 v[4:5], s[36:37], 0, v[4:5]
	v_lshl_add_u64 v[130:131], v[4:5], 0, s[18:19]
	s_add_i32 m0, s25, 0x2000
	v_lshlrev_b32_e32 v1, 6, v14
	v_lshlrev_b32_e32 v10, 1, v13
	v_lshlrev_b64 v[2:3], 9, v[2:3]
	global_load_lds_dwordx4 v[4:5], off
	s_add_i32 m0, s25, 0x4000
	s_nop 0
	global_load_lds_dwordx4 v[128:129], off
	s_add_i32 m0, s25, 0x6000
	s_nop 0
	global_load_lds_dwordx4 v[130:131], off
	v_or3_b32 v4, v1, v10, v2
	v_lshrrev_b32_e32 v132, 11, v4
	v_lshrrev_b32_e32 v133, 12, v4
	v_xor_b32_e32 v132, v132, v133
	v_and_b32_e32 v132, 1, v132
	v_mul_u32_u24_e32 v132, 0x1800, v132
	v_xor_b32_e32 v4, v4, v132
	v_mov_b32_e32 v5, v3
	v_lshlrev_b32_e32 v1, 6, v16
	v_lshlrev_b64 v[6:7], 9, v[6:7]
	v_lshl_add_u64 v[4:5], s[30:31], 0, v[4:5]
	s_add_i32 m0, s25, 0x8000
	v_or3_b32 v10, v1, v10, v6
	v_lshrrev_b32_e32 v132, 11, v10
	v_lshrrev_b32_e32 v133, 12, v10
	v_xor_b32_e32 v132, v132, v133
	v_and_b32_e32 v132, 1, v132
	v_mul_u32_u24_e32 v132, 0x1800, v132
	v_xor_b32_e32 v10, v10, v132
	v_mov_b32_e32 v11, v7
	global_load_lds_dwordx4 v[4:5], off
	v_lshl_add_u64 v[10:11], s[30:31], 0, v[10:11]
	s_add_i32 m0, s25, 0xa000
	v_lshl_add_u64 v[4:5], v[4:5], 0, s[10:11]
	global_load_lds_dwordx4 v[10:11], off
	s_add_i32 m0, s25, 0xc000
	s_add_i32 s33, 0, 0x8000
	global_load_lds_dwordx4 v[4:5], off
	v_lshl_add_u64 v[4:5], v[10:11], 0, s[10:11]
	s_add_i32 m0, s25, 0xe000
	v_lshlrev_b32_e32 v20, 13, v211
	global_load_lds_dwordx4 v[4:5], off
	s_cmp_lg_u32 s33, -1
	v_lshl_or_b32 v1, v206, 8, v20
	s_cselect_b32 s41, s33, 0
	s_and_b32 s2, s2, 1
	v_lshlrev_b32_e32 v4, 4, v197
	v_add_u32_e32 v216, 0, v1
	s_lshl_b32 s2, s2, 6
	v_and_b32_e32 v1, 32, v197
	v_and_b32_e32 v5, 0x70, v4
	v_bitop3_b32 v225, v194, v4, s58 bitop3:0x78
	v_or3_b32 v4, s2, v1, v13
	s_and_b32 s2, s3, 1
	s_lshl_b32 s2, s2, 6
	v_or3_b32 v1, s2, v1, v13
	v_add_u32_e32 v0, 32, v0
	v_and_b32_e32 v18, 0xc0, v212
	s_waitcnt vmcnt(0)
	v_lshl_or_b32 v6, v1, 1, v6
	v_ashrrev_i32_e32 v1, 31, v0
	s_waitcnt lgkmcnt(0)
	s_barrier
; __device__ __forceinline__ int v_rd_base(int lane) { return ((lane & 3) << 3) | (((lane >> 2) & 3) << 6) | (((lane >> 4) & 1) << 5) | (((lane >> 5) & 1) << 8); }
; #define RAWBAR() do { asm volatile("s_waitcnt lgkmcnt(0)" ::: "memory"); __builtin_amdgcn_s_barrier(); asm volatile("" ::: "memory"); } while (0)
; #define RAWBAR() do { asm volatile("s_waitcnt lgkmcnt(0)" ::: "memory"); __builtin_amdgcn_s_barrier(); asm volatile("" ::: "memory"); } while (0)
; #define RAWBAR() do { asm volatile("s_waitcnt lgkmcnt(0)" ::: "memory"); __builtin_amdgcn_s_barrier(); asm volatile("" ::: "memory"); } while (0)
; template <int MODE> ...
;     ...
;   f32x16 o[8] = {}; bf16x8 qr[8]; float lsum = 0.f;
;   const bf16* Qw = Qb + (long)(g * 32 + r32) * 128 + hi * 8;
; #pragma unroll
;   for (int d0 = 0; d0 < 8; ++d0) qr[d0] = St::ld8(Qw + d0 * 16);
;   const int vb0 = (int)(uintptr_t)V_lds + v_rd_base(lane) + 2 * kh * 4096;
;   const int krow = 32 * kh + r32;
;   typedef __attribute__((address_space(3))) unsigned lds_u32;
;   const int wu = __builtin_amdgcn_readfirstlane(wid);
;   long gk[2], gv[2];
; #pragma unroll
;   for (int c = 0; c < 2; ++c) { const int q = wu + 8 * c;
;     const int r = 4 * q + (lane >> 4), pch = lane & 15; gk[c] = (long)r * 128 + ((pch ^ (r & 7)) * 8);
;     const int st = 2 * q + (lane >> 5), kk = (st >> 2) * 8 + ((lane >> 2) & 7), k = (kk & ~0xC) | ((kk & 4) << 1) | ((kk & 8) >> 1), cc = (st & 3) * 32 + (lane & 3) * 8;
;     gv[c] = (long)k * 256 + cc; }
;     ...
;   const int NT = seq / KVBLK;
;   STAGE(0, 0); asm volatile("s_waitcnt vmcnt(0)" ::: "memory"); RAWBAR();
;   if (false) __builtin_amdgcn_s_setprio(1);
;   for (int j = 0; j < NT; ++j) {
;     const int buf = j & 1;
;     if (j + 1 < NT) { STAGE((j + 1) * KVBLK, buf ^ 1); }
;     const char* Kb = K_lds + buf * 16384;
;     f32x16 pe = {}, po = {};
; #pragma unroll
;     for (int d0 = 0; d0 < 8; d0 += 2) {
;       const bf16x8 k0 = *reinterpret_cast<const bf16x8*>(Kb + KSWZ(krow, (d0 * 16 + hi * 8) * 2));
;       const bf16x8 k1 = *reinterpret_cast<const bf16x8*>(Kb + KSWZ(krow, ((d0 + 1) * 16 + hi * 8) * 2));
;       pe = __builtin_amdgcn_mfma_f32_32x32x16_bf16(k0, qr[d0], pe, 0, 0, 0);
;       po = __builtin_amdgcn_mfma_f32_32x32x16_bf16(k1, qr[d0 + 1], po, 0, 0, 0); }
	v_add_u32_e32 v10, s41, v18
	v_readlane_b32 s84, v251, 28
	v_lshlrev_b64 v[0:1], 8, v[0:1]
	v_add3_u32 v10, v10, v17, v19
	v_lshl_or_b32 v2, v4, 1, v2
	v_readlane_b32 s85, v251, 29
	v_or_b32_e32 v0, v0, v15
	v_mov_b32_e32 v215, 0
	s_mov_b32 s25, 0
	v_add3_u32 v214, v10, v12, v20
	v_bitop3_b32 v223, v194, v5, 32 bitop3:0x36
	v_bitop3_b32 v222, v194, v5, 64 bitop3:0x36
	v_bitop3_b32 v221, v194, v5, s43 bitop3:0x36
	v_bitop3_b32 v220, v194, v5, s59 bitop3:0x36
	v_bitop3_b32 v219, v194, v5, s60 bitop3:0x36
	v_bitop3_b32 v218, v194, v5, s56 bitop3:0x36
	v_bitop3_b32 v217, v194, v5, s61 bitop3:0x36
	v_lshl_add_u64 v[198:199], s[84:85], 0, v[2:3]
	v_lshl_add_u64 v[200:201], s[84:85], 0, v[6:7]
	v_lshl_add_u64 v[202:203], s[6:7], 0, v[8:9]
	v_lshl_add_u64 v[204:205], s[6:7], 0, v[0:1]
	v_mov_b32_e32 v0, 0
	v_mov_b32_e32 v1, v215
	v_mov_b32_e32 v2, v215
	v_mov_b32_e32 v3, v215
	v_mov_b32_e32 v4, v215
	v_mov_b32_e32 v5, v215
	v_mov_b32_e32 v6, v215
	v_mov_b32_e32 v7, v215
	v_mov_b32_e32 v8, v215
	v_mov_b32_e32 v9, v215
	v_mov_b32_e32 v10, v215
	v_mov_b32_e32 v11, v215
	v_mov_b32_e32 v12, v215
	v_mov_b32_e32 v13, v215
	v_mov_b32_e32 v14, v215
	v_mov_b32_e32 v15, v215
	v_mov_b32_e32 v16, 0
	v_mov_b32_e32 v17, v215
	v_mov_b32_e32 v18, v215
	v_mov_b32_e32 v19, v215
	v_mov_b32_e32 v20, v215
	v_mov_b32_e32 v21, v215
	v_mov_b32_e32 v22, v215
	v_mov_b32_e32 v23, v215
	v_mov_b32_e32 v24, v215
	v_mov_b32_e32 v25, v215
	v_mov_b32_e32 v26, v215
	v_mov_b32_e32 v27, v215
	v_mov_b32_e32 v28, v215
	v_mov_b32_e32 v29, v215
	v_mov_b32_e32 v30, v215
	v_mov_b32_e32 v31, v215
	v_mov_b32_e32 v32, 0
	v_mov_b32_e32 v33, v215
	v_mov_b32_e32 v34, v215
	v_mov_b32_e32 v35, v215
	v_mov_b32_e32 v36, v215
	v_mov_b32_e32 v37, v215
	v_mov_b32_e32 v38, v215
	v_mov_b32_e32 v39, v215
	v_mov_b32_e32 v40, v215
	v_mov_b32_e32 v41, v215
	v_mov_b32_e32 v42, v215
	v_mov_b32_e32 v43, v215
	v_mov_b32_e32 v44, v215
	v_mov_b32_e32 v45, v215
	v_mov_b32_e32 v46, v215
	v_mov_b32_e32 v47, v215
	v_mov_b32_e32 v48, 0
	v_mov_b32_e32 v49, v215
	v_mov_b32_e32 v50, v215
	v_mov_b32_e32 v51, v215
	v_mov_b32_e32 v52, v215
	v_mov_b32_e32 v53, v215
	v_mov_b32_e32 v54, v215
	v_mov_b32_e32 v55, v215
	v_mov_b32_e32 v56, v215
	v_mov_b32_e32 v57, v215
	v_mov_b32_e32 v58, v215
	v_mov_b32_e32 v59, v215
	v_mov_b32_e32 v60, v215
	v_mov_b32_e32 v61, v215
	v_mov_b32_e32 v62, v215
	v_mov_b32_e32 v63, v215
	v_mov_b32_e32 v64, 0
	v_mov_b32_e32 v65, v215
	v_mov_b32_e32 v66, v215
	v_mov_b32_e32 v67, v215
	v_mov_b32_e32 v68, v215
	v_mov_b32_e32 v69, v215
	v_mov_b32_e32 v70, v215
	v_mov_b32_e32 v71, v215
	v_mov_b32_e32 v72, v215
	v_mov_b32_e32 v73, v215
	v_mov_b32_e32 v74, v215
	v_mov_b32_e32 v75, v215
	v_mov_b32_e32 v76, v215
	v_mov_b32_e32 v77, v215
	v_mov_b32_e32 v78, v215
	v_mov_b32_e32 v79, v215
	v_mov_b32_e32 v80, 0
	v_mov_b32_e32 v81, v215
	v_mov_b32_e32 v82, v215
	v_mov_b32_e32 v83, v215
	v_mov_b32_e32 v84, v215
	v_mov_b32_e32 v85, v215
	v_mov_b32_e32 v86, v215
	v_mov_b32_e32 v87, v215
	v_mov_b32_e32 v88, v215
	v_mov_b32_e32 v89, v215
	v_mov_b32_e32 v90, v215
	v_mov_b32_e32 v91, v215
	v_mov_b32_e32 v92, v215
	v_mov_b32_e32 v93, v215
	v_mov_b32_e32 v94, v215
	v_mov_b32_e32 v95, v215
	v_mov_b32_e32 v96, 0
	v_mov_b32_e32 v97, v215
	v_mov_b32_e32 v98, v215
	v_mov_b32_e32 v99, v215
	v_mov_b32_e32 v100, v215
	v_mov_b32_e32 v101, v215
	v_mov_b32_e32 v102, v215
	v_mov_b32_e32 v103, v215
	v_mov_b32_e32 v104, v215
	v_mov_b32_e32 v105, v215
	v_mov_b32_e32 v106, v215
	v_mov_b32_e32 v107, v215
	v_mov_b32_e32 v108, v215
	v_mov_b32_e32 v109, v215
	v_mov_b32_e32 v110, v215
	v_mov_b32_e32 v111, v215
	v_mov_b32_e32 v112, 0
	v_mov_b32_e32 v113, v215
	v_mov_b32_e32 v114, v215
	v_mov_b32_e32 v115, v215
	v_mov_b32_e32 v116, v215
	v_mov_b32_e32 v117, v215
	v_mov_b32_e32 v118, v215
	v_mov_b32_e32 v119, v215
	v_mov_b32_e32 v120, v215
	v_mov_b32_e32 v121, v215
	v_mov_b32_e32 v122, v215
	v_mov_b32_e32 v123, v215
	v_mov_b32_e32 v124, v215
	v_mov_b32_e32 v125, v215
	v_mov_b32_e32 v126, v215
	v_mov_b32_e32 v127, v215
	v_readlane_b32 s86, v251, 30
	v_readlane_b32 s87, v251, 31
	s_waitcnt vmcnt(0)
	v_subrev_u32_e32 v220, s6, v202
	v_subrev_u32_e32 v219, s6, v204
	v_subrev_u32_e32 v218, s84, v198
	v_subrev_u32_e32 v217, s84, v200
	v_lshrrev_b32_e32 v242, 11, v218
	v_lshrrev_b32_e32 v243, 12, v218
	v_xor_b32_e32 v242, v242, v243
	v_and_b32_e32 v242, 1, v242
	v_mul_u32_u24_e32 v242, 0x1800, v242
	v_xor_b32_e32 v218, v218, v242
	v_lshrrev_b32_e32 v242, 11, v217
	v_lshrrev_b32_e32 v243, 12, v217
	v_xor_b32_e32 v242, v242, v243
	v_and_b32_e32 v242, 1, v242
	v_mul_u32_u24_e32 v242, 0x1800, v242
	v_xor_b32_e32 v217, v217, v242
	v_add_u32_e32 v242, 0x100, v218
	v_add_u32_e32 v243, 0x100, v217
	s_add_u32 s86, s6, s26
	s_addc_u32 s87, s7, s27
	s_add_u32 s86, s86, 0x4000
	s_addc_u32 s87, s87, 0
	s_add_u32 s2, s84, s26
	s_addc_u32 s3, s85, s27
	s_add_u32 s2, s2, s12
	s_addc_u32 s3, s3, s13
	v_add_u32_e32 v225, v216, v225
	v_add_u32_e32 v223, v216, v223
	v_add_u32_e32 v222, v216, v222
	v_add_u32_e32 v221, v216, v221
	v_and_b32_e32 v202, 16, v197
	v_lshlrev_b32_e32 v202, 3, v202
	v_add_u32_e32 v221, v221, v202
	v_xor_b32_e32 v205, 0x80, v221
	v_add_u32_e32 v222, v222, v202
	v_xor_b32_e32 v204, 0x80, v222
	v_add_u32_e32 v223, v223, v202
	v_xor_b32_e32 v203, 0x80, v223
	v_add_u32_e32 v225, v225, v202
	v_xor_b32_e32 v202, 0x80, v225
	ds_read_b128 v[226:229], v225
	ds_read_b128 v[230:233], v223
	s_waitcnt lgkmcnt(0)
	v_mfma_f32_32x32x16_bf16 v[144:159], v[226:229], v[188:191], 0
	v_mfma_f32_32x32x16_bf16 v[144:159], v[230:233], v[184:187], v[144:159]
	ds_read_b128 v[226:229], v222
	ds_read_b128 v[230:233], v221
	s_waitcnt lgkmcnt(0)
	v_mfma_f32_32x32x16_bf16 v[144:159], v[226:229], v[180:183], v[144:159]
	v_mfma_f32_32x32x16_bf16 v[144:159], v[230:233], v[176:179], v[144:159]
	ds_read_b128 v[226:229], v202
	ds_read_b128 v[230:233], v203
	s_waitcnt lgkmcnt(0)
	v_mfma_f32_32x32x16_bf16 v[144:159], v[226:229], v[172:175], v[144:159]
	v_mfma_f32_32x32x16_bf16 v[144:159], v[230:233], v[168:171], v[144:159]
	ds_read_b128 v[226:229], v204
	ds_read_b128 v[230:233], v205
	s_waitcnt lgkmcnt(0)
	v_mfma_f32_32x32x16_bf16 v[144:159], v[226:229], v[164:167], v[144:159]
	v_mfma_f32_32x32x16_bf16 v[144:159], v[230:233], v[160:163], v[144:159]
	s_mov_b32 s84, 0
	s_barrier
	s_cmp_lt_u32 s24, 0x1000
	s_cbranch_scc0 .LattnBpre_m0
; #define SBAR() __builtin_amdgcn_sched_barrier(0)
; #define PVR(S, DA, DB, vbase) do { S[0] = tr_read<v_rd_off(DA, 0, 0)>(vbase); S[1] = tr_read<v_rd_off(DA, 0, 1)>(vbase); S[2] = tr_read<v_rd_off(DB, 0, 0)>(vbase); S[3] = tr_read<v_rd_off(DB, 0, 1)>(vbase); \
;     S[4] = tr_read<v_rd_off(DA, 1, 0)>(vbase); S[5] = tr_read<v_rd_off(DA, 1, 1)>(vbase); S[6] = tr_read<v_rd_off(DB, 1, 0)>(vbase); S[7] = tr_read<v_rd_off(DB, 1, 1)>(vbase); } while (0)
; #define RAWBAR() do { asm volatile("s_waitcnt lgkmcnt(0)" ::: "memory"); __builtin_amdgcn_s_barrier(); asm volatile("" ::: "memory"); } while (0)
; #define RAWBAR() do { asm volatile("s_waitcnt lgkmcnt(0)" ::: "memory"); __builtin_amdgcn_s_barrier(); asm volatile("" ::: "memory"); } while (0)
; #define RAWBAR() do { asm volatile("s_waitcnt lgkmcnt(0)" ::: "memory"); __builtin_amdgcn_s_barrier(); asm volatile("" ::: "memory"); } while (0)
; #define RAWBAR() do { asm volatile("s_waitcnt lgkmcnt(0)" ::: "memory"); __builtin_amdgcn_s_barrier(); asm volatile("" ::: "memory"); } while (0)
; #define RAWBAR() do { asm volatile("s_waitcnt lgkmcnt(0)" ::: "memory"); __builtin_amdgcn_s_barrier(); asm volatile("" ::: "memory"); } while (0)
; template <int MODE> ...
;     ...
;     if (j + 1 < NT) { STAGE((j + 1) * KVBLK, buf ^ 1); }
;     const char* Kb = K_lds + buf * 16384;
;     f32x16 pe = {}, po = {};
; #pragma unroll
;     for (int d0 = 0; d0 < 8; d0 += 2) {
;       const bf16x8 k0 = *reinterpret_cast<const bf16x8*>(Kb + KSWZ(krow, (d0 * 16 + hi * 8) * 2));
;       const bf16x8 k1 = *reinterpret_cast<const bf16x8*>(Kb + KSWZ(krow, ((d0 + 1) * 16 + hi * 8) * 2));
;       pe = __builtin_amdgcn_mfma_f32_32x32x16_bf16(k0, qr[d0], pe, 0, 0, 0);
;       po = __builtin_amdgcn_mfma_f32_32x32x16_bf16(k1, qr[d0 + 1], po, 0, 0, 0); }
;     const int vo = vb0 + buf * 32768;
;     s16x4 R0_[8], R1_[8];
;     PVR(R0_, 0, 1, vo);
;     f32x16 p;
; #pragma unroll
;     for (int r = 0; r < 16; ++r) p[r] = __builtin_amdgcn_exp2f(fmaf(pe[r] + po[r], C, negMc));
;     float ps = 0.f;
; #pragma unroll
;     for (int r = 0; r < 16; ++r) ps += p[r];
;     lsum += ps;
;     const bf16x8 own0 = pk8(p, 0), own1 = pk8(p, 8);
;     SBAR();
;     PV_TAIL4(o, vo, vo + 16384, own0, own1);
;     asm volatile("s_waitcnt vmcnt(0)" ::: "memory");
;     RAWBAR();
.LBB0_1019:
	ds_read_b128 v[226:229], v225 offset:16384
	ds_read_b128 v[230:233], v223 offset:16384
	ds_read_b128 v[234:237], v222 offset:16384
	ds_read_b128 v[238:241], v221 offset:16384
	s_mov_b32 m0, s24
	s_nop 0
	global_load_lds_dwordx4 v220, s[86:87] sc1
	s_add_i32 m0, s24, 0x2000
	s_nop 0
	global_load_lds_dwordx4 v219, s[86:87] sc1
	v_exp_f32_e32 v144, v144
	v_exp_f32_e32 v145, v145
	v_exp_f32_e32 v146, v146
	v_exp_f32_e32 v147, v147
	s_waitcnt lgkmcnt(2)
	v_mfma_f32_32x32x16_bf16 v[128:143], v[226:229], v[188:191], 0
	v_mfma_f32_32x32x16_bf16 v[128:143], v[230:233], v[184:187], v[128:143]
	ds_read_b128 v[226:229], v202 offset:16384
	ds_read_b128 v[230:233], v203 offset:16384
	v_exp_f32_e32 v148, v148
	v_exp_f32_e32 v149, v149
	v_exp_f32_e32 v150, v150
	v_exp_f32_e32 v151, v151
	v_add_f32_e32 v246, v144, v145
	v_add_f32_e32 v246, v146, v246
	v_add_f32_e32 v246, v147, v246
	s_waitcnt lgkmcnt(2)
	v_mfma_f32_32x32x16_bf16 v[128:143], v[234:237], v[180:183], v[128:143]
	v_mfma_f32_32x32x16_bf16 v[128:143], v[238:241], v[176:179], v[128:143]
	ds_read_b128 v[234:237], v204 offset:16384
	ds_read_b128 v[238:241], v205 offset:16384
	v_exp_f32_e32 v152, v152
	v_exp_f32_e32 v153, v153
	v_exp_f32_e32 v154, v154
	v_exp_f32_e32 v155, v155
	v_add_f32_e32 v246, v148, v246
	v_add_f32_e32 v246, v149, v246
	v_add_f32_e32 v246, v150, v246
	v_add_f32_e32 v246, v151, v246
	s_waitcnt lgkmcnt(2)
	v_mfma_f32_32x32x16_bf16 v[128:143], v[226:229], v[172:175], v[128:143]
	v_mfma_f32_32x32x16_bf16 v[128:143], v[230:233], v[168:171], v[128:143]
	v_exp_f32_e32 v156, v156
	v_exp_f32_e32 v157, v157
	v_exp_f32_e32 v158, v158
	v_exp_f32_e32 v159, v159
	v_add_f32_e32 v246, v152, v246
	v_add_f32_e32 v246, v153, v246
	v_add_f32_e32 v246, v154, v246
	v_add_f32_e32 v246, v155, v246
	v_cvt_pk_bf16_f32 v226, v144, v145
	v_cvt_pk_bf16_f32 v227, v146, v147
	v_cvt_pk_bf16_f32 v228, v148, v149
	v_cvt_pk_bf16_f32 v229, v150, v151
	s_waitcnt lgkmcnt(0)
	v_mfma_f32_32x32x16_bf16 v[128:143], v[234:237], v[164:167], v[128:143]
	v_mfma_f32_32x32x16_bf16 v[128:143], v[238:241], v[160:163], v[128:143]
	v_add_u32_e32 v245, s84, v214
	s_add_i32 s85, s84, 0x8000
	s_cmp_eq_u32 s85, 0x18000
	s_cselect_b32 s85, 0, s85
	ds_read_b64_tr_b16 v[234:235], v245 offset:0
	ds_read_b64_tr_b16 v[236:237], v245 offset:2048
	ds_read_b64_tr_b16 v[238:239], v245 offset:512
	ds_read_b64_tr_b16 v[240:241], v245 offset:2560
	ds_read_b64_tr_b16 v[144:145], v245 offset:4096
	ds_read_b64_tr_b16 v[146:147], v245 offset:6144
	ds_read_b64_tr_b16 v[148:149], v245 offset:4608
	ds_read_b64_tr_b16 v[150:151], v245 offset:6656
	v_add_f32_e32 v246, v156, v246
	v_add_f32_e32 v246, v157, v246
	v_add_f32_e32 v246, v158, v246
	v_add_f32_e32 v246, v159, v246
	v_cvt_pk_bf16_f32 v230, v152, v153
	v_cvt_pk_bf16_f32 v231, v154, v155
	v_cvt_pk_bf16_f32 v232, v156, v157
	v_cvt_pk_bf16_f32 v233, v158, v159
	v_add_f32_e32 v215, v215, v246
	ds_read_b64_tr_b16 v[152:153], v245 offset:1024
	ds_read_b64_tr_b16 v[154:155], v245 offset:3072
	ds_read_b64_tr_b16 v[156:157], v245 offset:1536
	ds_read_b64_tr_b16 v[158:159], v245 offset:3584
	s_waitcnt lgkmcnt(8)
	v_mfma_f32_32x32x16_bf16 v[112:127], v[226:229], v[234:237], v[112:127]
	v_mfma_f32_32x32x16_bf16 v[96:111], v[226:229], v[238:241], v[96:111]
	ds_read_b64_tr_b16 v[234:235], v245 offset:5120
	ds_read_b64_tr_b16 v[236:237], v245 offset:7168
	ds_read_b64_tr_b16 v[238:239], v245 offset:5632
	ds_read_b64_tr_b16 v[240:241], v245 offset:7680
	s_add_i32 s41, s85, s24
	s_add_i32 m0, s41, 0x8000
	s_nop 0
	global_load_lds_dwordx4 v218, s[2:3] sc1
	s_waitcnt lgkmcnt(8)
	v_mfma_f32_32x32x16_bf16 v[112:127], v[230:233], v[144:147], v[112:127]
	v_mfma_f32_32x32x16_bf16 v[96:111], v[230:233], v[148:151], v[96:111]
	ds_read_b64_tr_b16 v[144:145], v245 offset:16384
	ds_read_b64_tr_b16 v[146:147], v245 offset:18432
	ds_read_b64_tr_b16 v[148:149], v245 offset:16896
	ds_read_b64_tr_b16 v[150:151], v245 offset:18944
	s_add_i32 s41, s85, s24
	s_add_i32 m0, s41, 0xa000
	s_nop 0
	global_load_lds_dwordx4 v217, s[2:3] sc1
	s_waitcnt lgkmcnt(8)
	v_mfma_f32_32x32x16_bf16 v[80:95], v[226:229], v[152:155], v[80:95]
	v_mfma_f32_32x32x16_bf16 v[64:79], v[226:229], v[156:159], v[64:79]
	ds_read_b64_tr_b16 v[152:153], v245 offset:20480
	ds_read_b64_tr_b16 v[154:155], v245 offset:22528
	ds_read_b64_tr_b16 v[156:157], v245 offset:20992
	ds_read_b64_tr_b16 v[158:159], v245 offset:23040
	s_add_i32 s41, s85, s24
	s_add_i32 m0, s41, 0xc000
	s_nop 0
	global_load_lds_dwordx4 v242, s[2:3] sc1
	s_waitcnt lgkmcnt(8)
	v_mfma_f32_32x32x16_bf16 v[80:95], v[230:233], v[234:237], v[80:95]
	v_mfma_f32_32x32x16_bf16 v[64:79], v[230:233], v[238:241], v[64:79]
	ds_read_b64_tr_b16 v[234:235], v245 offset:17408
	ds_read_b64_tr_b16 v[236:237], v245 offset:19456
	ds_read_b64_tr_b16 v[238:239], v245 offset:17920
	ds_read_b64_tr_b16 v[240:241], v245 offset:19968
	s_add_i32 s41, s85, s24
	s_add_i32 m0, s41, 0xe000
	s_nop 0
	global_load_lds_dwordx4 v243, s[2:3] sc1
	s_waitcnt lgkmcnt(8)
	v_mfma_f32_32x32x16_bf16 v[48:63], v[226:229], v[144:147], v[48:63]
	v_mfma_f32_32x32x16_bf16 v[32:47], v[226:229], v[148:151], v[32:47]
	ds_read_b64_tr_b16 v[144:145], v245 offset:21504
	ds_read_b64_tr_b16 v[146:147], v245 offset:23552
	ds_read_b64_tr_b16 v[148:149], v245 offset:22016
	ds_read_b64_tr_b16 v[150:151], v245 offset:24064
	s_waitcnt lgkmcnt(8)
	v_mfma_f32_32x32x16_bf16 v[48:63], v[230:233], v[152:155], v[48:63]
	v_mfma_f32_32x32x16_bf16 v[32:47], v[230:233], v[156:159], v[32:47]
	s_waitcnt lgkmcnt(0)
	v_mfma_f32_32x32x16_bf16 v[16:31], v[226:229], v[234:237], v[16:31]
	s_waitcnt vmcnt(0)
	s_barrier
; #define SBAR() __builtin_amdgcn_sched_barrier(0)
; #define PVR(S, DA, DB, vbase) do { S[0] = tr_read<v_rd_off(DA, 0, 0)>(vbase); S[1] = tr_read<v_rd_off(DA, 0, 1)>(vbase); S[2] = tr_read<v_rd_off(DB, 0, 0)>(vbase); S[3] = tr_read<v_rd_off(DB, 0, 1)>(vbase); \
;     S[4] = tr_read<v_rd_off(DA, 1, 0)>(vbase); S[5] = tr_read<v_rd_off(DA, 1, 1)>(vbase); S[6] = tr_read<v_rd_off(DB, 1, 0)>(vbase); S[7] = tr_read<v_rd_off(DB, 1, 1)>(vbase); } while (0)
; #define RAWBAR() do { asm volatile("s_waitcnt lgkmcnt(0)" ::: "memory"); __builtin_amdgcn_s_barrier(); asm volatile("" ::: "memory"); } while (0)
; #define RAWBAR() do { asm volatile("s_waitcnt lgkmcnt(0)" ::: "memory"); __builtin_amdgcn_s_barrier(); asm volatile("" ::: "memory"); } while (0)
; #define RAWBAR() do { asm volatile("s_waitcnt lgkmcnt(0)" ::: "memory"); __builtin_amdgcn_s_barrier(); asm volatile("" ::: "memory"); } while (0)
; #define RAWBAR() do { asm volatile("s_waitcnt lgkmcnt(0)" ::: "memory"); __builtin_amdgcn_s_barrier(); asm volatile("" ::: "memory"); } while (0)
; #define RAWBAR() do { asm volatile("s_waitcnt lgkmcnt(0)" ::: "memory"); __builtin_amdgcn_s_barrier(); asm volatile("" ::: "memory"); } while (0)
; template <int MODE> ...
;     ...
;   for (int j = 0; j < NT; ++j) {
;     const int buf = j & 1;
;     if (j + 1 < NT) { STAGE((j + 1) * KVBLK, buf ^ 1); }
;     const char* Kb = K_lds + buf * 16384;
;     f32x16 pe = {}, po = {};
; #pragma unroll
;     for (int d0 = 0; d0 < 8; d0 += 2) {
;       const bf16x8 k0 = *reinterpret_cast<const bf16x8*>(Kb + KSWZ(krow, (d0 * 16 + hi * 8) * 2));
;       const bf16x8 k1 = *reinterpret_cast<const bf16x8*>(Kb + KSWZ(krow, ((d0 + 1) * 16 + hi * 8) * 2));
;       pe = __builtin_amdgcn_mfma_f32_32x32x16_bf16(k0, qr[d0], pe, 0, 0, 0);
;       po = __builtin_amdgcn_mfma_f32_32x32x16_bf16(k1, qr[d0 + 1], po, 0, 0, 0); }
;     const int vo = vb0 + buf * 32768;
;     s16x4 R0_[8], R1_[8];
;     PVR(R0_, 0, 1, vo);
;     f32x16 p;
; #pragma unroll
;     for (int r = 0; r < 16; ++r) p[r] = __builtin_amdgcn_exp2f(fmaf(pe[r] + po[r], C, negMc));
;     float ps = 0.f;
; #pragma unroll
;     for (int r = 0; r < 16; ++r) ps += p[r];
;     lsum += ps;
;     const bf16x8 own0 = pk8(p, 0), own1 = pk8(p, 8);
;     SBAR();
;     PV_TAIL4(o, vo, vo + 16384, own0, own1);
;     asm volatile("s_waitcnt vmcnt(0)" ::: "memory");
;     RAWBAR();
;   }
	s_add_u32 s86, s86, 0x4000
	s_addc_u32 s87, s87, 0
	s_add_u32 s2, s2, 0x8000
	s_addc_u32 s3, s3, 0
	v_mfma_f32_32x32x16_bf16 v[0:15], v[226:229], v[238:241], v[0:15]
	v_mfma_f32_32x32x16_bf16 v[16:31], v[230:233], v[144:147], v[16:31]
	v_mfma_f32_32x32x16_bf16 v[0:15], v[230:233], v[148:151], v[0:15]
	s_add_i32 s84, s84, 0x8000
	s_cmp_eq_u32 s84, 0x18000
	s_cselect_b32 s84, 0, s84
	ds_read_b128 v[226:229], v225 offset:0
	ds_read_b128 v[230:233], v223 offset:0
	ds_read_b128 v[234:237], v222 offset:0
	ds_read_b128 v[238:241], v221 offset:0
	s_add_i32 m0, s24, 0x4000
	s_nop 0
	global_load_lds_dwordx4 v220, s[86:87] sc1
	s_add_i32 m0, s24, 0x6000
	s_nop 0
	global_load_lds_dwordx4 v219, s[86:87] sc1
	v_exp_f32_e32 v128, v128
	v_exp_f32_e32 v129, v129
	v_exp_f32_e32 v130, v130
	v_exp_f32_e32 v131, v131
	s_waitcnt lgkmcnt(2)
	v_mfma_f32_32x32x16_bf16 v[144:159], v[226:229], v[188:191], 0
	v_mfma_f32_32x32x16_bf16 v[144:159], v[230:233], v[184:187], v[144:159]
	ds_read_b128 v[226:229], v202 offset:0
	ds_read_b128 v[230:233], v203 offset:0
	v_exp_f32_e32 v132, v132
	v_exp_f32_e32 v133, v133
	v_exp_f32_e32 v134, v134
	v_exp_f32_e32 v135, v135
	v_add_f32_e32 v246, v128, v129
	v_add_f32_e32 v246, v130, v246
	v_add_f32_e32 v246, v131, v246
	s_waitcnt lgkmcnt(2)
	v_mfma_f32_32x32x16_bf16 v[144:159], v[234:237], v[180:183], v[144:159]
	v_mfma_f32_32x32x16_bf16 v[144:159], v[238:241], v[176:179], v[144:159]
	ds_read_b128 v[234:237], v204 offset:0
	ds_read_b128 v[238:241], v205 offset:0
	v_exp_f32_e32 v136, v136
	v_exp_f32_e32 v137, v137
	v_exp_f32_e32 v138, v138
	v_exp_f32_e32 v139, v139
	v_add_f32_e32 v246, v132, v246
	v_add_f32_e32 v246, v133, v246
	v_add_f32_e32 v246, v134, v246
	v_add_f32_e32 v246, v135, v246
	s_waitcnt lgkmcnt(2)
	v_mfma_f32_32x32x16_bf16 v[144:159], v[226:229], v[172:175], v[144:159]
	v_mfma_f32_32x32x16_bf16 v[144:159], v[230:233], v[168:171], v[144:159]
	v_exp_f32_e32 v140, v140
	v_exp_f32_e32 v141, v141
	v_exp_f32_e32 v142, v142
	v_exp_f32_e32 v143, v143
	v_add_f32_e32 v246, v136, v246
	v_add_f32_e32 v246, v137, v246
	v_add_f32_e32 v246, v138, v246
	v_add_f32_e32 v246, v139, v246
	v_cvt_pk_bf16_f32 v226, v128, v129
	v_cvt_pk_bf16_f32 v227, v130, v131
	v_cvt_pk_bf16_f32 v228, v132, v133
	v_cvt_pk_bf16_f32 v229, v134, v135
	s_waitcnt lgkmcnt(0)
	v_mfma_f32_32x32x16_bf16 v[144:159], v[234:237], v[164:167], v[144:159]
	v_mfma_f32_32x32x16_bf16 v[144:159], v[238:241], v[160:163], v[144:159]
	v_add_u32_e32 v245, s84, v214
	s_add_i32 s85, s84, 0x8000
	s_cmp_eq_u32 s85, 0x18000
	s_cselect_b32 s85, 0, s85
	ds_read_b64_tr_b16 v[234:235], v245 offset:0
	ds_read_b64_tr_b16 v[236:237], v245 offset:2048
	ds_read_b64_tr_b16 v[238:239], v245 offset:512
	ds_read_b64_tr_b16 v[240:241], v245 offset:2560
	ds_read_b64_tr_b16 v[128:129], v245 offset:4096
	ds_read_b64_tr_b16 v[130:131], v245 offset:6144
	ds_read_b64_tr_b16 v[132:133], v245 offset:4608
	ds_read_b64_tr_b16 v[134:135], v245 offset:6656
	v_add_f32_e32 v246, v140, v246
	v_add_f32_e32 v246, v141, v246
	v_add_f32_e32 v246, v142, v246
	v_add_f32_e32 v246, v143, v246
	v_cvt_pk_bf16_f32 v230, v136, v137
	v_cvt_pk_bf16_f32 v231, v138, v139
	v_cvt_pk_bf16_f32 v232, v140, v141
	v_cvt_pk_bf16_f32 v233, v142, v143
	v_add_f32_e32 v215, v215, v246
	ds_read_b64_tr_b16 v[136:137], v245 offset:1024
	ds_read_b64_tr_b16 v[138:139], v245 offset:3072
	ds_read_b64_tr_b16 v[140:141], v245 offset:1536
	ds_read_b64_tr_b16 v[142:143], v245 offset:3584
	s_waitcnt lgkmcnt(8)
	v_mfma_f32_32x32x16_bf16 v[112:127], v[226:229], v[234:237], v[112:127]
	v_mfma_f32_32x32x16_bf16 v[96:111], v[226:229], v[238:241], v[96:111]
	ds_read_b64_tr_b16 v[234:235], v245 offset:5120
	ds_read_b64_tr_b16 v[236:237], v245 offset:7168
	ds_read_b64_tr_b16 v[238:239], v245 offset:5632
	ds_read_b64_tr_b16 v[240:241], v245 offset:7680
	s_add_i32 s41, s85, s24
	s_add_i32 m0, s41, 0x8000
	s_nop 0
	global_load_lds_dwordx4 v218, s[2:3] sc1
	s_waitcnt lgkmcnt(8)
	v_mfma_f32_32x32x16_bf16 v[112:127], v[230:233], v[128:131], v[112:127]
	v_mfma_f32_32x32x16_bf16 v[96:111], v[230:233], v[132:135], v[96:111]
	ds_read_b64_tr_b16 v[128:129], v245 offset:16384
	ds_read_b64_tr_b16 v[130:131], v245 offset:18432
	ds_read_b64_tr_b16 v[132:133], v245 offset:16896
	ds_read_b64_tr_b16 v[134:135], v245 offset:18944
	s_add_i32 s41, s85, s24
	s_add_i32 m0, s41, 0xa000
	s_nop 0
	global_load_lds_dwordx4 v217, s[2:3] sc1
	s_waitcnt lgkmcnt(8)
	v_mfma_f32_32x32x16_bf16 v[80:95], v[226:229], v[136:139], v[80:95]
	v_mfma_f32_32x32x16_bf16 v[64:79], v[226:229], v[140:143], v[64:79]
	ds_read_b64_tr_b16 v[136:137], v245 offset:20480
	ds_read_b64_tr_b16 v[138:139], v245 offset:22528
	ds_read_b64_tr_b16 v[140:141], v245 offset:20992
	ds_read_b64_tr_b16 v[142:143], v245 offset:23040
	s_add_i32 s41, s85, s24
	s_add_i32 m0, s41, 0xc000
	s_nop 0
	global_load_lds_dwordx4 v242, s[2:3] sc1
	s_waitcnt lgkmcnt(8)
	v_mfma_f32_32x32x16_bf16 v[80:95], v[230:233], v[234:237], v[80:95]
	v_mfma_f32_32x32x16_bf16 v[64:79], v[230:233], v[238:241], v[64:79]
	ds_read_b64_tr_b16 v[234:235], v245 offset:17408
	ds_read_b64_tr_b16 v[236:237], v245 offset:19456
	ds_read_b64_tr_b16 v[238:239], v245 offset:17920
	ds_read_b64_tr_b16 v[240:241], v245 offset:19968
	s_add_i32 s41, s85, s24
	s_add_i32 m0, s41, 0xe000
	s_nop 0
	global_load_lds_dwordx4 v243, s[2:3] sc1
	s_waitcnt lgkmcnt(8)
	v_mfma_f32_32x32x16_bf16 v[48:63], v[226:229], v[128:131], v[48:63]
	v_mfma_f32_32x32x16_bf16 v[32:47], v[226:229], v[132:135], v[32:47]
	ds_read_b64_tr_b16 v[128:129], v245 offset:21504
	ds_read_b64_tr_b16 v[130:131], v245 offset:23552
	ds_read_b64_tr_b16 v[132:133], v245 offset:22016
	ds_read_b64_tr_b16 v[134:135], v245 offset:24064
	s_waitcnt lgkmcnt(8)
	v_mfma_f32_32x32x16_bf16 v[48:63], v[230:233], v[136:139], v[48:63]
	v_mfma_f32_32x32x16_bf16 v[32:47], v[230:233], v[140:143], v[32:47]
	s_waitcnt lgkmcnt(0)
	v_mfma_f32_32x32x16_bf16 v[16:31], v[226:229], v[234:237], v[16:31]
	s_waitcnt vmcnt(0)
	s_barrier
	s_add_u32 s86, s86, 0x4000
	s_addc_u32 s87, s87, 0
	s_add_u32 s2, s2, 0x8000
	s_addc_u32 s3, s3, 0
	v_mfma_f32_32x32x16_bf16 v[0:15], v[226:229], v[238:241], v[0:15]
	v_mfma_f32_32x32x16_bf16 v[16:31], v[230:233], v[128:131], v[16:31]
	v_mfma_f32_32x32x16_bf16 v[0:15], v[230:233], v[132:135], v[0:15]
	s_add_i32 s84, s84, 0x8000
	s_cmp_eq_u32 s84, 0x18000
	s_cselect_b32 s84, 0, s84
	s_add_i32 s25, s25, 1
	s_cmpk_eq_i32 s25, 0x82
	s_cbranch_scc0 .LBB0_1019
	s_barrier
	s_branch .Lattn_join_m0

; #define SBAR() __builtin_amdgcn_sched_barrier(0)
; #define PVR(S, DA, DB, vbase) do { S[0] = tr_read<v_rd_off(DA, 0, 0)>(vbase); S[1] = tr_read<v_rd_off(DA, 0, 1)>(vbase); S[2] = tr_read<v_rd_off(DB, 0, 0)>(vbase); S[3] = tr_read<v_rd_off(DB, 0, 1)>(vbase); \
;     S[4] = tr_read<v_rd_off(DA, 1, 0)>(vbase); S[5] = tr_read<v_rd_off(DA, 1, 1)>(vbase); S[6] = tr_read<v_rd_off(DB, 1, 0)>(vbase); S[7] = tr_read<v_rd_off(DB, 1, 1)>(vbase); } while (0)
; #define RAWBAR() do { asm volatile("s_waitcnt lgkmcnt(0)" ::: "memory"); __builtin_amdgcn_s_barrier(); asm volatile("" ::: "memory"); } while (0)
; #define RAWBAR() do { asm volatile("s_waitcnt lgkmcnt(0)" ::: "memory"); __builtin_amdgcn_s_barrier(); asm volatile("" ::: "memory"); } while (0)
; #define RAWBAR() do { asm volatile("s_waitcnt lgkmcnt(0)" ::: "memory"); __builtin_amdgcn_s_barrier(); asm volatile("" ::: "memory"); } while (0)
; #define RAWBAR() do { asm volatile("s_waitcnt lgkmcnt(0)" ::: "memory"); __builtin_amdgcn_s_barrier(); asm volatile("" ::: "memory"); } while (0)
; #define RAWBAR() do { asm volatile("s_waitcnt lgkmcnt(0)" ::: "memory"); __builtin_amdgcn_s_barrier(); asm volatile("" ::: "memory"); } while (0)
; template <int MODE> ...
;     ...
;   for (int j = 0; j < NT; ++j) {
;     const int buf = j & 1;
;     if (j + 1 < NT) { STAGE((j + 1) * KVBLK, buf ^ 1); }
;     const char* Kb = K_lds + buf * 16384;
;     f32x16 pe = {}, po = {};
; #pragma unroll
;     for (int d0 = 0; d0 < 8; d0 += 2) {
;       const bf16x8 k0 = *reinterpret_cast<const bf16x8*>(Kb + KSWZ(krow, (d0 * 16 + hi * 8) * 2));
;       const bf16x8 k1 = *reinterpret_cast<const bf16x8*>(Kb + KSWZ(krow, ((d0 + 1) * 16 + hi * 8) * 2));
;       pe = __builtin_amdgcn_mfma_f32_32x32x16_bf16(k0, qr[d0], pe, 0, 0, 0);
;       po = __builtin_amdgcn_mfma_f32_32x32x16_bf16(k1, qr[d0 + 1], po, 0, 0, 0); }
;     const int vo = vb0 + buf * 32768;
;     s16x4 R0_[8], R1_[8];
;     PVR(R0_, 0, 1, vo);
;     f32x16 p;
; #pragma unroll
;     for (int r = 0; r < 16; ++r) p[r] = __builtin_amdgcn_exp2f(fmaf(pe[r] + po[r], C, negMc));
;     float ps = 0.f;
; #pragma unroll
;     for (int r = 0; r < 16; ++r) ps += p[r];
;     lsum += ps;
;     const bf16x8 own0 = pk8(p, 0), own1 = pk8(p, 8);
;     SBAR();
;     PV_TAIL4(o, vo, vo + 16384, own0, own1);
;     asm volatile("s_waitcnt vmcnt(0)" ::: "memory");
;     RAWBAR();
;   }
.LattnB_m0:
	ds_read_b128 v[226:229], v225 offset:16384
	ds_read_b128 v[230:233], v223 offset:16384
	ds_read_b128 v[234:237], v222 offset:16384
	ds_read_b128 v[238:241], v221 offset:16384
	v_exp_f32_e32 v144, v144
	v_exp_f32_e32 v145, v145
	v_exp_f32_e32 v146, v146
	v_exp_f32_e32 v147, v147
	s_waitcnt lgkmcnt(2)
	v_mfma_f32_32x32x16_bf16 v[128:143], v[226:229], v[188:191], 0
	v_mfma_f32_32x32x16_bf16 v[128:143], v[230:233], v[184:187], v[128:143]
	ds_read_b128 v[226:229], v202 offset:16384
	ds_read_b128 v[230:233], v203 offset:16384
	v_exp_f32_e32 v148, v148
	v_exp_f32_e32 v149, v149
	v_exp_f32_e32 v150, v150
	v_exp_f32_e32 v151, v151
	v_add_f32_e32 v246, v144, v145
	v_add_f32_e32 v246, v146, v246
	v_add_f32_e32 v246, v147, v246
	s_waitcnt lgkmcnt(2)
	v_mfma_f32_32x32x16_bf16 v[128:143], v[234:237], v[180:183], v[128:143]
	v_mfma_f32_32x32x16_bf16 v[128:143], v[238:241], v[176:179], v[128:143]
	ds_read_b128 v[234:237], v204 offset:16384
	ds_read_b128 v[238:241], v205 offset:16384
	v_exp_f32_e32 v152, v152
	v_exp_f32_e32 v153, v153
	v_exp_f32_e32 v154, v154
	v_exp_f32_e32 v155, v155
	v_add_f32_e32 v246, v148, v246
	v_add_f32_e32 v246, v149, v246
	v_add_f32_e32 v246, v150, v246
	v_add_f32_e32 v246, v151, v246
	s_waitcnt lgkmcnt(2)
	v_mfma_f32_32x32x16_bf16 v[128:143], v[226:229], v[172:175], v[128:143]
	v_mfma_f32_32x32x16_bf16 v[128:143], v[230:233], v[168:171], v[128:143]
	v_exp_f32_e32 v156, v156
	v_exp_f32_e32 v157, v157
	v_exp_f32_e32 v158, v158
	v_exp_f32_e32 v159, v159
	v_add_f32_e32 v246, v152, v246
	v_add_f32_e32 v246, v153, v246
	v_add_f32_e32 v246, v154, v246
	v_add_f32_e32 v246, v155, v246
	v_cvt_pk_bf16_f32 v226, v144, v145
	v_cvt_pk_bf16_f32 v227, v146, v147
	v_cvt_pk_bf16_f32 v228, v148, v149
	v_cvt_pk_bf16_f32 v229, v150, v151
	s_waitcnt lgkmcnt(0)
	v_mfma_f32_32x32x16_bf16 v[128:143], v[234:237], v[164:167], v[128:143]
	v_mfma_f32_32x32x16_bf16 v[128:143], v[238:241], v[160:163], v[128:143]
	s_waitcnt vmcnt(0)
	s_barrier
	s_add_u32 s86, s86, 0x4000
	s_addc_u32 s87, s87, 0
	s_add_u32 s2, s2, 0x8000
	s_addc_u32 s3, s3, 0
	s_add_i32 m0, s24, 0x4000
	s_nop 0
	global_load_lds_dwordx4 v220, s[86:87] sc1
	s_add_i32 m0, s24, 0x6000
	s_nop 0
	global_load_lds_dwordx4 v219, s[86:87] sc1
	v_add_u32_e32 v245, s84, v214
	s_sub_u32 s85, s84, 0x8000
	s_cmp_eq_u32 s84, 0
	s_cselect_b32 s85, 0x10000, s85
	ds_read_b64_tr_b16 v[234:235], v245 offset:0
	ds_read_b64_tr_b16 v[236:237], v245 offset:2048
	ds_read_b64_tr_b16 v[238:239], v245 offset:512
	ds_read_b64_tr_b16 v[240:241], v245 offset:2560
	ds_read_b64_tr_b16 v[144:145], v245 offset:4096
	ds_read_b64_tr_b16 v[146:147], v245 offset:6144
	ds_read_b64_tr_b16 v[148:149], v245 offset:4608
	ds_read_b64_tr_b16 v[150:151], v245 offset:6656
	v_add_f32_e32 v246, v156, v246
	v_add_f32_e32 v246, v157, v246
	v_add_f32_e32 v246, v158, v246
	v_add_f32_e32 v246, v159, v246
	v_cvt_pk_bf16_f32 v230, v152, v153
	v_cvt_pk_bf16_f32 v231, v154, v155
	v_cvt_pk_bf16_f32 v232, v156, v157
	v_cvt_pk_bf16_f32 v233, v158, v159
	v_add_f32_e32 v215, v215, v246
	ds_read_b64_tr_b16 v[152:153], v245 offset:1024
	ds_read_b64_tr_b16 v[154:155], v245 offset:3072
	ds_read_b64_tr_b16 v[156:157], v245 offset:1536
	ds_read_b64_tr_b16 v[158:159], v245 offset:3584
	s_waitcnt lgkmcnt(8)
	v_mfma_f32_32x32x16_bf16 v[112:127], v[226:229], v[234:237], v[112:127]
	v_mfma_f32_32x32x16_bf16 v[96:111], v[226:229], v[238:241], v[96:111]
	ds_read_b64_tr_b16 v[234:235], v245 offset:5120
	ds_read_b64_tr_b16 v[236:237], v245 offset:7168
	ds_read_b64_tr_b16 v[238:239], v245 offset:5632
	ds_read_b64_tr_b16 v[240:241], v245 offset:7680
	s_add_i32 s41, s85, s24
	s_add_i32 m0, s41, 0x8000
	s_nop 0
	global_load_lds_dwordx4 v218, s[2:3] sc1
	s_waitcnt lgkmcnt(8)
	v_mfma_f32_32x32x16_bf16 v[112:127], v[230:233], v[144:147], v[112:127]
	v_mfma_f32_32x32x16_bf16 v[96:111], v[230:233], v[148:151], v[96:111]
	ds_read_b64_tr_b16 v[144:145], v245 offset:16384
	ds_read_b64_tr_b16 v[146:147], v245 offset:18432
	ds_read_b64_tr_b16 v[148:149], v245 offset:16896
	ds_read_b64_tr_b16 v[150:151], v245 offset:18944
	s_add_i32 s41, s85, s24
	s_add_i32 m0, s41, 0xa000
	s_nop 0
	global_load_lds_dwordx4 v217, s[2:3] sc1
	s_waitcnt lgkmcnt(8)
	v_mfma_f32_32x32x16_bf16 v[80:95], v[226:229], v[152:155], v[80:95]
	v_mfma_f32_32x32x16_bf16 v[64:79], v[226:229], v[156:159], v[64:79]
	ds_read_b64_tr_b16 v[152:153], v245 offset:20480
	ds_read_b64_tr_b16 v[154:155], v245 offset:22528
	ds_read_b64_tr_b16 v[156:157], v245 offset:20992
	ds_read_b64_tr_b16 v[158:159], v245 offset:23040
	s_add_i32 s41, s85, s24
	s_add_i32 m0, s41, 0xc000
	s_nop 0
	global_load_lds_dwordx4 v242, s[2:3] sc1
	s_waitcnt lgkmcnt(8)
	v_mfma_f32_32x32x16_bf16 v[80:95], v[230:233], v[234:237], v[80:95]
	v_mfma_f32_32x32x16_bf16 v[64:79], v[230:233], v[238:241], v[64:79]
	ds_read_b64_tr_b16 v[234:235], v245 offset:17408
	ds_read_b64_tr_b16 v[236:237], v245 offset:19456
	ds_read_b64_tr_b16 v[238:239], v245 offset:17920
	ds_read_b64_tr_b16 v[240:241], v245 offset:19968
	s_add_i32 s41, s85, s24
	s_add_i32 m0, s41, 0xe000
	s_nop 0
	global_load_lds_dwordx4 v243, s[2:3] sc1
	s_waitcnt lgkmcnt(8)
	v_mfma_f32_32x32x16_bf16 v[48:63], v[226:229], v[144:147], v[48:63]
	v_mfma_f32_32x32x16_bf16 v[32:47], v[226:229], v[148:151], v[32:47]
	ds_read_b64_tr_b16 v[144:145], v245 offset:21504
	ds_read_b64_tr_b16 v[146:147], v245 offset:23552
	ds_read_b64_tr_b16 v[148:149], v245 offset:22016
	ds_read_b64_tr_b16 v[150:151], v245 offset:24064
	s_waitcnt lgkmcnt(8)
	v_mfma_f32_32x32x16_bf16 v[48:63], v[230:233], v[152:155], v[48:63]
	v_mfma_f32_32x32x16_bf16 v[32:47], v[230:233], v[156:159], v[32:47]
	s_waitcnt lgkmcnt(0)
; #define SBAR() __builtin_amdgcn_sched_barrier(0)
; #define PVR(S, DA, DB, vbase) do { S[0] = tr_read<v_rd_off(DA, 0, 0)>(vbase); S[1] = tr_read<v_rd_off(DA, 0, 1)>(vbase); S[2] = tr_read<v_rd_off(DB, 0, 0)>(vbase); S[3] = tr_read<v_rd_off(DB, 0, 1)>(vbase); \
;     S[4] = tr_read<v_rd_off(DA, 1, 0)>(vbase); S[5] = tr_read<v_rd_off(DA, 1, 1)>(vbase); S[6] = tr_read<v_rd_off(DB, 1, 0)>(vbase); S[7] = tr_read<v_rd_off(DB, 1, 1)>(vbase); } while (0)
; #define RAWBAR() do { asm volatile("s_waitcnt lgkmcnt(0)" ::: "memory"); __builtin_amdgcn_s_barrier(); asm volatile("" ::: "memory"); } while (0)
; #define RAWBAR() do { asm volatile("s_waitcnt lgkmcnt(0)" ::: "memory"); __builtin_amdgcn_s_barrier(); asm volatile("" ::: "memory"); } while (0)
; #define RAWBAR() do { asm volatile("s_waitcnt lgkmcnt(0)" ::: "memory"); __builtin_amdgcn_s_barrier(); asm volatile("" ::: "memory"); } while (0)
; #define RAWBAR() do { asm volatile("s_waitcnt lgkmcnt(0)" ::: "memory"); __builtin_amdgcn_s_barrier(); asm volatile("" ::: "memory"); } while (0)
; #define RAWBAR() do { asm volatile("s_waitcnt lgkmcnt(0)" ::: "memory"); __builtin_amdgcn_s_barrier(); asm volatile("" ::: "memory"); } while (0)
; template <int MODE> ...
;     ...
;   for (int j = 0; j < NT; ++j) {
;     const int buf = j & 1;
;     if (j + 1 < NT) { STAGE((j + 1) * KVBLK, buf ^ 1); }
;     const char* Kb = K_lds + buf * 16384;
;     f32x16 pe = {}, po = {};
; #pragma unroll
;     for (int d0 = 0; d0 < 8; d0 += 2) {
;       const bf16x8 k0 = *reinterpret_cast<const bf16x8*>(Kb + KSWZ(krow, (d0 * 16 + hi * 8) * 2));
;       const bf16x8 k1 = *reinterpret_cast<const bf16x8*>(Kb + KSWZ(krow, ((d0 + 1) * 16 + hi * 8) * 2));
;       pe = __builtin_amdgcn_mfma_f32_32x32x16_bf16(k0, qr[d0], pe, 0, 0, 0);
;       po = __builtin_amdgcn_mfma_f32_32x32x16_bf16(k1, qr[d0 + 1], po, 0, 0, 0); }
;     const int vo = vb0 + buf * 32768;
;     s16x4 R0_[8], R1_[8];
;     PVR(R0_, 0, 1, vo);
;     f32x16 p;
; #pragma unroll
;     for (int r = 0; r < 16; ++r) p[r] = __builtin_amdgcn_exp2f(fmaf(pe[r] + po[r], C, negMc));
;     float ps = 0.f;
; #pragma unroll
;     for (int r = 0; r < 16; ++r) ps += p[r];
;     lsum += ps;
;     const bf16x8 own0 = pk8(p, 0), own1 = pk8(p, 8);
;     SBAR();
;     PV_TAIL4(o, vo, vo + 16384, own0, own1);
;     asm volatile("s_waitcnt vmcnt(0)" ::: "memory");
;     RAWBAR();
;   }
	v_mfma_f32_32x32x16_bf16 v[16:31], v[226:229], v[234:237], v[16:31]
	v_mfma_f32_32x32x16_bf16 v[0:15], v[226:229], v[238:241], v[0:15]
	v_mfma_f32_32x32x16_bf16 v[16:31], v[230:233], v[144:147], v[16:31]
	v_mfma_f32_32x32x16_bf16 v[0:15], v[230:233], v[148:151], v[0:15]
	s_add_i32 s84, s84, 0x8000
	s_cmp_eq_u32 s84, 0x18000
	s_cselect_b32 s84, 0, s84
	ds_read_b128 v[226:229], v225 offset:0
	ds_read_b128 v[230:233], v223 offset:0
	ds_read_b128 v[234:237], v222 offset:0
	ds_read_b128 v[238:241], v221 offset:0
	v_exp_f32_e32 v128, v128
	v_exp_f32_e32 v129, v129
	v_exp_f32_e32 v130, v130
	v_exp_f32_e32 v131, v131
	s_waitcnt lgkmcnt(2)
	v_mfma_f32_32x32x16_bf16 v[144:159], v[226:229], v[188:191], 0
	v_mfma_f32_32x32x16_bf16 v[144:159], v[230:233], v[184:187], v[144:159]
	ds_read_b128 v[226:229], v202 offset:0
	ds_read_b128 v[230:233], v203 offset:0
	v_exp_f32_e32 v132, v132
	v_exp_f32_e32 v133, v133
	v_exp_f32_e32 v134, v134
	v_exp_f32_e32 v135, v135
	v_add_f32_e32 v246, v128, v129
	v_add_f32_e32 v246, v130, v246
	v_add_f32_e32 v246, v131, v246
	s_waitcnt lgkmcnt(2)
	v_mfma_f32_32x32x16_bf16 v[144:159], v[234:237], v[180:183], v[144:159]
	v_mfma_f32_32x32x16_bf16 v[144:159], v[238:241], v[176:179], v[144:159]
	ds_read_b128 v[234:237], v204 offset:0
	ds_read_b128 v[238:241], v205 offset:0
	v_exp_f32_e32 v136, v136
	v_exp_f32_e32 v137, v137
	v_exp_f32_e32 v138, v138
	v_exp_f32_e32 v139, v139
	v_add_f32_e32 v246, v132, v246
	v_add_f32_e32 v246, v133, v246
	v_add_f32_e32 v246, v134, v246
	v_add_f32_e32 v246, v135, v246
	s_waitcnt lgkmcnt(2)
	v_mfma_f32_32x32x16_bf16 v[144:159], v[226:229], v[172:175], v[144:159]
	v_mfma_f32_32x32x16_bf16 v[144:159], v[230:233], v[168:171], v[144:159]
	v_exp_f32_e32 v140, v140
	v_exp_f32_e32 v141, v141
	v_exp_f32_e32 v142, v142
	v_exp_f32_e32 v143, v143
	v_add_f32_e32 v246, v136, v246
	v_add_f32_e32 v246, v137, v246
	v_add_f32_e32 v246, v138, v246
	v_add_f32_e32 v246, v139, v246
	v_cvt_pk_bf16_f32 v226, v128, v129
	v_cvt_pk_bf16_f32 v227, v130, v131
	v_cvt_pk_bf16_f32 v228, v132, v133
	v_cvt_pk_bf16_f32 v229, v134, v135
	s_waitcnt lgkmcnt(0)
	v_mfma_f32_32x32x16_bf16 v[144:159], v[234:237], v[164:167], v[144:159]
	v_mfma_f32_32x32x16_bf16 v[144:159], v[238:241], v[160:163], v[144:159]
	s_waitcnt vmcnt(0)
	s_barrier
	s_add_u32 s86, s86, 0x4000
	s_addc_u32 s87, s87, 0
	s_add_u32 s2, s2, 0x8000
	s_addc_u32 s3, s3, 0
	s_mov_b32 m0, s24
	s_nop 0
	global_load_lds_dwordx4 v220, s[86:87] sc1
	s_add_i32 m0, s24, 0x2000
	s_nop 0
	global_load_lds_dwordx4 v219, s[86:87] sc1
	v_add_u32_e32 v245, s84, v214
	s_sub_u32 s85, s84, 0x8000
	s_cmp_eq_u32 s84, 0
	s_cselect_b32 s85, 0x10000, s85
	ds_read_b64_tr_b16 v[234:235], v245 offset:0
	ds_read_b64_tr_b16 v[236:237], v245 offset:2048
	ds_read_b64_tr_b16 v[238:239], v245 offset:512
	ds_read_b64_tr_b16 v[240:241], v245 offset:2560
	ds_read_b64_tr_b16 v[128:129], v245 offset:4096
	ds_read_b64_tr_b16 v[130:131], v245 offset:6144
	ds_read_b64_tr_b16 v[132:133], v245 offset:4608
	ds_read_b64_tr_b16 v[134:135], v245 offset:6656
	v_add_f32_e32 v246, v140, v246
	v_add_f32_e32 v246, v141, v246
	v_add_f32_e32 v246, v142, v246
	v_add_f32_e32 v246, v143, v246
	v_cvt_pk_bf16_f32 v230, v136, v137
	v_cvt_pk_bf16_f32 v231, v138, v139
	v_cvt_pk_bf16_f32 v232, v140, v141
	v_cvt_pk_bf16_f32 v233, v142, v143
	v_add_f32_e32 v215, v215, v246
	ds_read_b64_tr_b16 v[136:137], v245 offset:1024
	ds_read_b64_tr_b16 v[138:139], v245 offset:3072
	ds_read_b64_tr_b16 v[140:141], v245 offset:1536
	ds_read_b64_tr_b16 v[142:143], v245 offset:3584
	s_waitcnt lgkmcnt(8)
	v_mfma_f32_32x32x16_bf16 v[112:127], v[226:229], v[234:237], v[112:127]
	v_mfma_f32_32x32x16_bf16 v[96:111], v[226:229], v[238:241], v[96:111]
	ds_read_b64_tr_b16 v[234:235], v245 offset:5120
	ds_read_b64_tr_b16 v[236:237], v245 offset:7168
	ds_read_b64_tr_b16 v[238:239], v245 offset:5632
	ds_read_b64_tr_b16 v[240:241], v245 offset:7680
	s_add_i32 s41, s85, s24
	s_add_i32 m0, s41, 0x8000
	s_nop 0
	global_load_lds_dwordx4 v218, s[2:3] sc1
	s_waitcnt lgkmcnt(8)
	v_mfma_f32_32x32x16_bf16 v[112:127], v[230:233], v[128:131], v[112:127]
	v_mfma_f32_32x32x16_bf16 v[96:111], v[230:233], v[132:135], v[96:111]
	ds_read_b64_tr_b16 v[128:129], v245 offset:16384
	ds_read_b64_tr_b16 v[130:131], v245 offset:18432
	ds_read_b64_tr_b16 v[132:133], v245 offset:16896
	ds_read_b64_tr_b16 v[134:135], v245 offset:18944
	s_add_i32 s41, s85, s24
	s_add_i32 m0, s41, 0xa000
	s_nop 0
	global_load_lds_dwordx4 v217, s[2:3] sc1
	s_waitcnt lgkmcnt(8)
	v_mfma_f32_32x32x16_bf16 v[80:95], v[226:229], v[136:139], v[80:95]
	v_mfma_f32_32x32x16_bf16 v[64:79], v[226:229], v[140:143], v[64:79]
	ds_read_b64_tr_b16 v[136:137], v245 offset:20480
	ds_read_b64_tr_b16 v[138:139], v245 offset:22528
	ds_read_b64_tr_b16 v[140:141], v245 offset:20992
	ds_read_b64_tr_b16 v[142:143], v245 offset:23040
	s_add_i32 s41, s85, s24
	s_add_i32 m0, s41, 0xc000
	s_nop 0
	global_load_lds_dwordx4 v242, s[2:3] sc1
	s_waitcnt lgkmcnt(8)
	v_mfma_f32_32x32x16_bf16 v[80:95], v[230:233], v[234:237], v[80:95]
	v_mfma_f32_32x32x16_bf16 v[64:79], v[230:233], v[238:241], v[64:79]
	ds_read_b64_tr_b16 v[234:235], v245 offset:17408
	ds_read_b64_tr_b16 v[236:237], v245 offset:19456
	ds_read_b64_tr_b16 v[238:239], v245 offset:17920
	ds_read_b64_tr_b16 v[240:241], v245 offset:19968
	s_add_i32 s41, s85, s24
	s_add_i32 m0, s41, 0xe000
	s_nop 0
	global_load_lds_dwordx4 v243, s[2:3] sc1
	s_waitcnt lgkmcnt(8)
	v_mfma_f32_32x32x16_bf16 v[48:63], v[226:229], v[128:131], v[48:63]
	v_mfma_f32_32x32x16_bf16 v[32:47], v[226:229], v[132:135], v[32:47]
	ds_read_b64_tr_b16 v[128:129], v245 offset:21504
	ds_read_b64_tr_b16 v[130:131], v245 offset:23552
	ds_read_b64_tr_b16 v[132:133], v245 offset:22016
	ds_read_b64_tr_b16 v[134:135], v245 offset:24064
	s_waitcnt lgkmcnt(8)
	v_mfma_f32_32x32x16_bf16 v[48:63], v[230:233], v[136:139], v[48:63]
	v_mfma_f32_32x32x16_bf16 v[32:47], v[230:233], v[140:143], v[32:47]
	s_waitcnt lgkmcnt(0)
	v_mfma_f32_32x32x16_bf16 v[16:31], v[226:229], v[234:237], v[16:31]
	v_mfma_f32_32x32x16_bf16 v[0:15], v[226:229], v[238:241], v[0:15]
	v_mfma_f32_32x32x16_bf16 v[16:31], v[230:233], v[128:131], v[16:31]
	v_mfma_f32_32x32x16_bf16 v[0:15], v[230:233], v[132:135], v[0:15]
	s_add_i32 s84, s84, 0x8000
	s_cmp_eq_u32 s84, 0x18000
	s_cselect_b32 s84, 0, s84
	s_add_i32 s25, s25, 1
	s_cmpk_eq_i32 s25, 0x82
	s_cbranch_scc0 .LattnB_m0
	s_waitcnt vmcnt(0)
	s_barrier

; __device__ __forceinline__ int crow(int r, int hi) { return (r & 3) + 8 * (r >> 2) + 4 * hi; }
; #define XS_WRITE(OV, BASE) do { float* xs_ = (float*)(lds + (BASE)) + ((g * 4) * 64 + lane) * 16; \
;     _Pragma("unroll") for (int d0 = 0; d0 < 4; ++d0) { float* xp = xs_ + d0 * 64 * 16; \
;       _Pragma("unroll") for (int q4 = 0; q4 < 4; ++q4) *(f32x4v*)(xp + 4 * q4) = (f32x4v){OV[d0][4 * q4], OV[d0][4 * q4 + 1], OV[d0][4 * q4 + 2], OV[d0][4 * q4 + 3]}; } } while (0)
; #define XS_WRITE(OV, BASE) do { float* xs_ = (float*)(lds + (BASE)) + ((g * 4) * 64 + lane) * 16; \
;     _Pragma("unroll") for (int d0 = 0; d0 < 4; ++d0) { float* xp = xs_ + d0 * 64 * 16; \
;       _Pragma("unroll") for (int q4 = 0; q4 < 4; ++q4) *(f32x4v*)(xp + 4 * q4) = (f32x4v){OV[d0][4 * q4], OV[d0][4 * q4 + 1], OV[d0][4 * q4 + 2], OV[d0][4 * q4 + 3]}; } } while (0)
; template <int MODE> ...
;     ...
;   f32x16* olo = o; f32x16* ohi = o + 4;
;   if (kh) { XS_WRITE(olo, 0); } else { XS_WRITE(ohi, 65536); }
;   __syncthreads();
;   if (kh) { XS_ADD(ohi, 65536);
; #pragma unroll
;     for (int d0 = 0; d0 < 4; ++d0) o[d0] = o[4 + d0]; }
;   else { XS_ADD(olo, 0); }
;     ...
;   float rli[16];
; #pragma unroll
;   for (int r = 0; r < 16; ++r) { const int row = crow(r, hi); const float* lp = L_lds + (g * 4) * 32 + row; rli[r] = __builtin_amdgcn_rcpf((lp[0] + lp[32]) + (lp[64] + lp[96])); }
.LBB0_1022:
	s_or_b64 exec, exec, s[24:25]
	v_add3_u32 v80, v129, v128, v130
	ds_read_b128 v[64:67], v80
	ds_read_b128 v[68:71], v80 offset:16
	ds_read_b128 v[72:75], v80 offset:32
	ds_read_b128 v[76:79], v80 offset:48
	s_ashr_i32 s24, s40, 3
	s_ashr_i32 s25, s24, 31
	s_waitcnt lgkmcnt(2)
	v_add_f32_e32 v68, v52, v68
	v_add_f32_e32 v64, v48, v64
	v_add_f32_e32 v65, v49, v65
	v_add_f32_e32 v66, v50, v66
	v_add_f32_e32 v67, v51, v67
	ds_read_b128 v[48:51], v80 offset:4096
	v_add_f32_e32 v69, v53, v69
	v_add_f32_e32 v70, v54, v70
	v_add_f32_e32 v71, v55, v71
	ds_read_b128 v[52:55], v80 offset:4112
	s_waitcnt lgkmcnt(1)
	v_add_f32_e32 v48, v32, v48
	v_add_f32_e32 v49, v33, v49
	v_add_f32_e32 v50, v34, v50
	v_add_f32_e32 v51, v35, v51
	ds_read_b128 v[32:35], v80 offset:4128
	s_waitcnt lgkmcnt(1)
	v_add_f32_e32 v52, v36, v52
	v_add_f32_e32 v53, v37, v53
	v_add_f32_e32 v54, v38, v54
	v_add_f32_e32 v55, v39, v55
	ds_read_b128 v[36:39], v80 offset:4144
	s_waitcnt lgkmcnt(1)
	v_add_f32_e32 v40, v40, v32
	v_add_f32_e32 v41, v41, v33
	v_add_f32_e32 v42, v42, v34
	v_add_f32_e32 v43, v43, v35
	ds_read_b128 v[32:35], v80 offset:8192
	s_waitcnt lgkmcnt(1)
	v_add_f32_e32 v44, v44, v36
	v_add_f32_e32 v45, v45, v37
	v_add_f32_e32 v46, v46, v38
	v_add_f32_e32 v47, v47, v39
	ds_read_b128 v[36:39], v80 offset:8208
	s_waitcnt lgkmcnt(1)
	v_add_f32_e32 v32, v16, v32
	v_add_f32_e32 v33, v17, v33
	v_add_f32_e32 v34, v18, v34
	v_add_f32_e32 v35, v19, v35
	ds_read_b128 v[16:19], v80 offset:8224
	s_waitcnt lgkmcnt(1)
	v_add_f32_e32 v36, v20, v36
	v_add_f32_e32 v37, v21, v37
	v_add_f32_e32 v38, v22, v38
	v_add_f32_e32 v39, v23, v39
	ds_read_b128 v[20:23], v80 offset:8240
	v_add_f32_e32 v56, v56, v72
	v_add_f32_e32 v57, v57, v73
	v_add_f32_e32 v58, v58, v74
	v_add_f32_e32 v59, v59, v75
	s_waitcnt lgkmcnt(1)
	v_add_f32_e32 v72, v24, v16
	v_add_f32_e32 v73, v25, v17
	v_add_f32_e32 v74, v26, v18
	v_add_f32_e32 v75, v27, v19
	ds_read_b128 v[16:19], v80 offset:12288
	v_add_f32_e32 v60, v60, v76
	v_add_f32_e32 v61, v61, v77
	v_add_f32_e32 v62, v62, v78
	v_add_f32_e32 v63, v63, v79
	s_waitcnt lgkmcnt(1)
	v_add_f32_e32 v76, v28, v20
	v_add_f32_e32 v77, v29, v21
	v_add_f32_e32 v78, v30, v22
	v_add_f32_e32 v79, v31, v23
	ds_read_b128 v[20:23], v80 offset:12304
	s_lshl_b32 s2, s40, 8
	s_and_b32 s94, s2, 0x700
	s_lshl_b64 s[2:3], s[24:25], 27
	s_lshl_b64 s[28:29], s[28:29], 20
	s_waitcnt lgkmcnt(1)
	v_add_f32_e32 v81, v0, v16
	v_add_f32_e32 v82, v1, v17
	v_add_f32_e32 v83, v2, v18
	v_add_f32_e32 v84, v3, v19
	ds_read_b128 v[0:3], v80 offset:12320
	s_add_u32 s2, s38, s2
	s_addc_u32 s3, s39, s3
	s_add_u32 s2, s2, s28
	s_waitcnt lgkmcnt(1)
	v_add_f32_e32 v85, v4, v20
	v_add_f32_e32 v86, v5, v21
	v_add_f32_e32 v87, v6, v22
	v_add_f32_e32 v88, v7, v23
	ds_read_b128 v[4:7], v80 offset:12336
	s_addc_u32 s3, s3, s29
	s_lshl_b32 s25, s94, 2
	s_add_u32 s28, s2, s25
	s_waitcnt lgkmcnt(1)
	v_add_f32_e32 v80, v8, v0
	v_and_b32_e32 v0, 0x3fffff80, v197
	s_addc_u32 s29, s3, 0
	v_lshlrev_b32_e32 v0, 2, v0
	s_add_i32 s25, 0, 0x20000
	v_add3_u32 v96, s25, v0, v194
	v_add_f32_e32 v89, v9, v1
	v_add_f32_e32 v90, v10, v2
	v_add_f32_e32 v91, v11, v3
	s_waitcnt lgkmcnt(0)
	v_add_f32_e32 v92, v12, v4
	v_add_f32_e32 v93, v13, v5
	v_add_f32_e32 v94, v14, v6
	v_add_f32_e32 v95, v15, v7
	ds_read_b128 v[0:3], v96 offset:128
	ds_read_b128 v[4:7], v96
	ds_read_b128 v[8:11], v96 offset:32
	ds_read_b128 v[12:15], v96 offset:256
	ds_read_b128 v[16:19], v96 offset:384
	ds_read_b128 v[20:23], v96 offset:160
	s_waitcnt lgkmcnt(4)
	v_add_f32_e32 v0, v4, v0
	ds_read_b128 v[24:27], v96 offset:288
	ds_read_b128 v[28:31], v96 offset:416
	v_ashrrev_i32_e32 v197, 31, v196
	s_waitcnt lgkmcnt(3)
	v_add_f32_e32 v4, v12, v16
	v_add_f32_e32 v0, v0, v4
	v_rcp_f32_e32 v97, v0
	v_add_f32_e32 v0, v5, v1
	v_add_f32_e32 v1, v13, v17
	v_add_f32_e32 v0, v0, v1
	v_rcp_f32_e32 v98, v0
	v_add_f32_e32 v0, v6, v2
	v_add_f32_e32 v1, v14, v18
	v_add_f32_e32 v0, v0, v1
	v_rcp_f32_e32 v99, v0
	v_add_f32_e32 v0, v7, v3
	v_add_f32_e32 v1, v15, v19
	v_add_f32_e32 v0, v0, v1
	v_rcp_f32_e32 v100, v0
	s_waitcnt lgkmcnt(2)
	v_add_f32_e32 v0, v8, v20
	s_waitcnt lgkmcnt(0)
	v_add_f32_e32 v1, v24, v28
	v_add_f32_e32 v0, v0, v1
	v_rcp_f32_e32 v101, v0
	v_add_f32_e32 v0, v9, v21
	v_add_f32_e32 v1, v25, v29
	v_add_f32_e32 v0, v0, v1
	v_rcp_f32_e32 v102, v0
	v_add_f32_e32 v0, v10, v22
	v_add_f32_e32 v1, v26, v30
	v_add_f32_e32 v0, v0, v1
	v_rcp_f32_e32 v103, v0
	v_add_f32_e32 v0, v11, v23
	v_add_f32_e32 v1, v27, v31
	v_add_f32_e32 v0, v0, v1
	v_rcp_f32_e32 v104, v0
	ds_read_b128 v[0:3], v96 offset:64
	ds_read_b128 v[4:7], v96 offset:192
	ds_read_b128 v[8:11], v96 offset:320
	ds_read_b128 v[12:15], v96 offset:448
	ds_read_b128 v[16:19], v96 offset:96
	ds_read_b128 v[20:23], v96 offset:224
	s_waitcnt lgkmcnt(4)
	v_add_f32_e32 v0, v0, v4
	ds_read_b128 v[24:27], v96 offset:352
	ds_read_b128 v[28:31], v96 offset:480
	s_waitcnt lgkmcnt(4)
	v_add_f32_e32 v4, v8, v12
	v_add_f32_e32 v0, v0, v4
	v_rcp_f32_e32 v4, v0
	v_add_f32_e32 v0, v1, v5
	v_add_f32_e32 v1, v9, v13
	v_add_f32_e32 v0, v0, v1
	v_rcp_f32_e32 v5, v0
	v_add_f32_e32 v0, v2, v6
	v_add_f32_e32 v1, v10, v14
	v_add_f32_e32 v0, v0, v1
	v_rcp_f32_e32 v6, v0
	v_add_f32_e32 v0, v3, v7
	v_add_f32_e32 v1, v11, v15
	v_add_f32_e32 v0, v0, v1
	v_rcp_f32_e32 v7, v0
	s_waitcnt lgkmcnt(2)
	v_add_f32_e32 v0, v16, v20
	s_waitcnt lgkmcnt(0)
; __device__ __forceinline__ int crow(int r, int hi) { return (r & 3) + 8 * (r >> 2) + 4 * hi; }
; template <int MODE> ...
;     ...
;   float rli[16];
; #pragma unroll
;   for (int r = 0; r < 16; ++r) { const int row = crow(r, hi); const float* lp = L_lds + (g * 4) * 32 + row; rli[r] = __builtin_amdgcn_rcpf((lp[0] + lp[32]) + (lp[64] + lp[96])); }
;   float* Ow = Ob + (long)(g * 32) * LDO + kh * 128;
;   if (MODE == 0) {
; #pragma unroll
;     for (int r = 0; r < 16; ++r) { const int orow = crow(r, hi);
; #pragma unroll
;       for (int d0 = 0; d0 < 4; ++d0) Ow[(long)orow * LDO + d0 * 32 + r32] = o[d0][r] * rli[r]; }
;     asm volatile("s_waitcnt vmcnt(0)" ::: "memory"); __syncthreads();
	v_add_f32_e32 v1, v24, v28
	v_add_f32_e32 v0, v0, v1
	v_rcp_f32_e32 v8, v0
	v_add_f32_e32 v0, v17, v21
	v_add_f32_e32 v1, v25, v29
	v_add_f32_e32 v0, v0, v1
	v_rcp_f32_e32 v9, v0
	v_add_f32_e32 v0, v18, v22
	v_add_f32_e32 v1, v26, v30
	v_add_f32_e32 v0, v0, v1
	v_rcp_f32_e32 v10, v0
	v_add_f32_e32 v0, v19, v23
	v_add_f32_e32 v1, v27, v31
	v_add_f32_e32 v0, v0, v1
	v_rcp_f32_e32 v11, v0
	v_lshlrev_b64 v[0:1], 13, v[196:197]
	v_lshl_add_u64 v[0:1], s[28:29], 0, v[0:1]
	v_lshlrev_b32_e32 v194, 9, v211
	v_lshl_add_u64 v[0:1], v[0:1], 0, v[194:195]
	v_lshlrev_b32_e32 v194, 2, v206
	v_lshlrev_b32_e32 v2, 15, v207
	v_lshl_add_u64 v[0:1], v[0:1], 0, v[194:195]
	v_mov_b32_e32 v3, v195
	v_lshl_add_u64 v[0:1], v[0:1], 0, v[2:3]
	v_mul_f32_e32 v2, v64, v97
	global_store_dword v[0:1], v2, off
	v_mul_f32_e32 v2, v48, v97
	global_store_dword v[0:1], v2, off offset:128
	v_mul_f32_e32 v2, v32, v97
	global_store_dword v[0:1], v2, off offset:256
	v_mul_f32_e32 v2, v81, v97
	global_store_dword v[0:1], v2, off offset:384
	v_add_co_u32_e32 v2, vcc, s57, v0
	v_mul_f32_e32 v12, v65, v98
	s_nop 0
	v_addc_co_u32_e32 v3, vcc, 0, v1, vcc
	global_store_dword v[2:3], v12, off
	v_mul_f32_e32 v12, v49, v98
	global_store_dword v[2:3], v12, off offset:128
	v_mul_f32_e32 v12, v33, v98
	global_store_dword v[2:3], v12, off offset:256
	v_mul_f32_e32 v12, v82, v98
	global_store_dword v[2:3], v12, off offset:384
	v_add_co_u32_e32 v2, vcc, s62, v0
	v_mul_f32_e32 v12, v66, v99
	s_nop 0
	v_addc_co_u32_e32 v3, vcc, 0, v1, vcc
	global_store_dword v[2:3], v12, off
	v_mul_f32_e32 v12, v50, v99
	global_store_dword v[2:3], v12, off offset:128
	v_mul_f32_e32 v12, v34, v99
	global_store_dword v[2:3], v12, off offset:256
	v_mul_f32_e32 v12, v83, v99
	global_store_dword v[2:3], v12, off offset:384
	v_add_co_u32_e32 v2, vcc, s66, v0
	v_mul_f32_e32 v12, v67, v100
	s_nop 0
	v_addc_co_u32_e32 v3, vcc, 0, v1, vcc
	global_store_dword v[2:3], v12, off
	v_mul_f32_e32 v12, v51, v100
	global_store_dword v[2:3], v12, off offset:128
	v_mul_f32_e32 v12, v35, v100
	global_store_dword v[2:3], v12, off offset:256
	v_mul_f32_e32 v12, v84, v100
	global_store_dword v[2:3], v12, off offset:384
	v_add_co_u32_e32 v2, vcc, s64, v0
	v_mul_f32_e32 v12, v68, v101
	s_nop 0
	v_addc_co_u32_e32 v3, vcc, 0, v1, vcc
	global_store_dword v[2:3], v12, off
	v_mul_f32_e32 v12, v52, v101
	global_store_dword v[2:3], v12, off offset:128
	v_mul_f32_e32 v12, v36, v101
	global_store_dword v[2:3], v12, off offset:256
	v_mul_f32_e32 v12, v85, v101
	global_store_dword v[2:3], v12, off offset:384
	v_add_co_u32_e32 v2, vcc, s67, v0
	v_mul_f32_e32 v12, v69, v102
	s_nop 0
	v_addc_co_u32_e32 v3, vcc, 0, v1, vcc
	global_store_dword v[2:3], v12, off
	v_mul_f32_e32 v12, v53, v102
	global_store_dword v[2:3], v12, off offset:128
	v_mul_f32_e32 v12, v37, v102
	global_store_dword v[2:3], v12, off offset:256
	v_mul_f32_e32 v12, v86, v102
	global_store_dword v[2:3], v12, off offset:384
	v_add_co_u32_e32 v2, vcc, s68, v0
	v_mul_f32_e32 v12, v70, v103
	s_nop 0
	v_addc_co_u32_e32 v3, vcc, 0, v1, vcc
	global_store_dword v[2:3], v12, off
	v_mul_f32_e32 v12, v54, v103
	global_store_dword v[2:3], v12, off offset:128
	v_mul_f32_e32 v12, v38, v103
	global_store_dword v[2:3], v12, off offset:256
	v_mul_f32_e32 v12, v87, v103
	global_store_dword v[2:3], v12, off offset:384
	v_add_co_u32_e32 v2, vcc, s69, v0
	v_mul_f32_e32 v12, v71, v104
	s_nop 0
	v_addc_co_u32_e32 v3, vcc, 0, v1, vcc
	global_store_dword v[2:3], v12, off
	v_mul_f32_e32 v12, v55, v104
	global_store_dword v[2:3], v12, off offset:128
	v_mul_f32_e32 v12, v39, v104
	global_store_dword v[2:3], v12, off offset:256
	v_mul_f32_e32 v12, v88, v104
	global_store_dword v[2:3], v12, off offset:384
	v_add_co_u32_e32 v2, vcc, s63, v0
	v_mul_f32_e32 v12, v56, v4
	s_nop 0
	v_addc_co_u32_e32 v3, vcc, 0, v1, vcc
	global_store_dword v[2:3], v12, off
	v_mul_f32_e32 v12, v40, v4
	global_store_dword v[2:3], v12, off offset:128
	v_mul_f32_e32 v12, v72, v4
	v_mul_f32_e32 v4, v80, v4
	global_store_dword v[2:3], v12, off offset:256
	global_store_dword v[2:3], v4, off offset:384
	v_add_co_u32_e32 v2, vcc, s70, v0
	v_mul_f32_e32 v4, v57, v5
	s_nop 0
	v_addc_co_u32_e32 v3, vcc, 0, v1, vcc
	global_store_dword v[2:3], v4, off
	v_mul_f32_e32 v4, v41, v5
	global_store_dword v[2:3], v4, off offset:128
	v_mul_f32_e32 v4, v73, v5
	global_store_dword v[2:3], v4, off offset:256
	v_mul_f32_e32 v4, v89, v5
	global_store_dword v[2:3], v4, off offset:384
	v_add_co_u32_e32 v2, vcc, s71, v0
	v_mul_f32_e32 v4, v58, v6
	s_nop 0
	v_addc_co_u32_e32 v3, vcc, 0, v1, vcc
	global_store_dword v[2:3], v4, off
	v_mul_f32_e32 v4, v42, v6
	global_store_dword v[2:3], v4, off offset:128
	v_mul_f32_e32 v4, v74, v6
	global_store_dword v[2:3], v4, off offset:256
	v_mul_f32_e32 v4, v90, v6
	global_store_dword v[2:3], v4, off offset:384
	v_add_co_u32_e32 v2, vcc, s72, v0
	v_mul_f32_e32 v4, v59, v7
	s_nop 0
	v_addc_co_u32_e32 v3, vcc, 0, v1, vcc
	global_store_dword v[2:3], v4, off
	v_mul_f32_e32 v4, v43, v7
	global_store_dword v[2:3], v4, off offset:128
	v_mul_f32_e32 v4, v75, v7
	global_store_dword v[2:3], v4, off offset:256
	v_mul_f32_e32 v4, v91, v7
	global_store_dword v[2:3], v4, off offset:384
	v_add_co_u32_e32 v2, vcc, s73, v0
	v_mul_f32_e32 v4, v60, v8
	s_nop 0
	v_addc_co_u32_e32 v3, vcc, 0, v1, vcc
	global_store_dword v[2:3], v4, off
	v_mul_f32_e32 v4, v44, v8
	global_store_dword v[2:3], v4, off offset:128
	v_mul_f32_e32 v4, v76, v8
	global_store_dword v[2:3], v4, off offset:256
	v_mul_f32_e32 v4, v92, v8
	global_store_dword v[2:3], v4, off offset:384
	v_add_co_u32_e32 v2, vcc, s74, v0
	v_mul_f32_e32 v4, v61, v9
	s_nop 0
	v_addc_co_u32_e32 v3, vcc, 0, v1, vcc
	global_store_dword v[2:3], v4, off
	v_mul_f32_e32 v4, v45, v9
	global_store_dword v[2:3], v4, off offset:128
	v_mul_f32_e32 v4, v77, v9
	global_store_dword v[2:3], v4, off offset:256
	v_mul_f32_e32 v4, v93, v9
	global_store_dword v[2:3], v4, off offset:384
	v_add_co_u32_e32 v2, vcc, s75, v0
	v_mul_f32_e32 v4, v62, v10
	s_nop 0
	v_addc_co_u32_e32 v3, vcc, 0, v1, vcc
	global_store_dword v[2:3], v4, off
	v_mul_f32_e32 v4, v46, v10
	global_store_dword v[2:3], v4, off offset:128
	v_mul_f32_e32 v4, v78, v10
	global_store_dword v[2:3], v4, off offset:256
	v_mul_f32_e32 v4, v94, v10
	v_add_co_u32_e32 v0, vcc, s76, v0
	global_store_dword v[2:3], v4, off offset:384
	v_mul_f32_e32 v2, v63, v11
	v_addc_co_u32_e32 v1, vcc, 0, v1, vcc
	global_store_dword v[0:1], v2, off
	v_mul_f32_e32 v2, v47, v11
	global_store_dword v[0:1], v2, off offset:128
	v_mul_f32_e32 v2, v79, v11
	global_store_dword v[0:1], v2, off offset:256
	v_mul_f32_e32 v2, v95, v11
	global_store_dword v[0:1], v2, off offset:384
	v_mov_b32_e32 v194, v224
	s_waitcnt vmcnt(0)
	s_waitcnt vmcnt(63) expcnt(7) lgkmcnt(15)
	s_barrier
; __device__ __forceinline__ int v_rd_base(int lane) { return ((lane & 3) << 3) | (((lane >> 2) & 3) << 6) | (((lane >> 4) & 1) << 5) | (((lane >> 5) & 1) << 8); }
; #define RAWBAR() do { asm volatile("s_waitcnt lgkmcnt(0)" ::: "memory"); __builtin_amdgcn_s_barrier(); asm volatile("" ::: "memory"); } while (0)
; #define RAWBAR() do { asm volatile("s_waitcnt lgkmcnt(0)" ::: "memory"); __builtin_amdgcn_s_barrier(); asm volatile("" ::: "memory"); } while (0)
; #define RAWBAR() do { asm volatile("s_waitcnt lgkmcnt(0)" ::: "memory"); __builtin_amdgcn_s_barrier(); asm volatile("" ::: "memory"); } while (0)
; #define RAWBAR() do { asm volatile("s_waitcnt lgkmcnt(0)" ::: "memory"); __builtin_amdgcn_s_barrier(); asm volatile("" ::: "memory"); } while (0)
; #define RAWBAR() do { asm volatile("s_waitcnt lgkmcnt(0)" ::: "memory"); __builtin_amdgcn_s_barrier(); asm volatile("" ::: "memory"); } while (0)
; #define RAWBAR() do { asm volatile("s_waitcnt lgkmcnt(0)" ::: "memory"); __builtin_amdgcn_s_barrier(); asm volatile("" ::: "memory"); } while (0)
; template <int MODE> ...
;     ...
;   const bf16* Qw = Qb + (long)(g * 32 + r32) * 128 + hi * 8;
; #pragma unroll
;   for (int d0 = 0; d0 < 8; ++d0) qr[d0] = St::ld8(Qw + d0 * 16);
;   const int vb0 = (int)(uintptr_t)V_lds + v_rd_base(lane) + 2 * kh * 4096;
;   const int krow = 32 * kh + r32;
;   typedef __attribute__((address_space(3))) unsigned lds_u32;
;   const int wu = __builtin_amdgcn_readfirstlane(wid);
;   long gk[2], gv[2];
; #pragma unroll
;   for (int c = 0; c < 2; ++c) { const int q = wu + 8 * c;
;     const int r = 4 * q + (lane >> 4), pch = lane & 15; gk[c] = (long)r * 128 + ((pch ^ (r & 7)) * 8);
;     const int st = 2 * q + (lane >> 5), kk = (st >> 2) * 8 + ((lane >> 2) & 7), k = (kk & ~0xC) | ((kk & 4) << 1) | ((kk & 8) >> 1), cc = (st & 3) * 32 + (lane & 3) * 8;
;     gv[c] = (long)k * 256 + cc; }
;     ...
;   const int NT = seq / KVBLK;
;   STAGE(0, 0); asm volatile("s_waitcnt vmcnt(0)" ::: "memory"); RAWBAR();
	v_mov_b32_e32 v199, v195
	v_ashrrev_i32_e32 v217, 7, v194
	v_and_b32_e32 v214, 31, v194
	v_lshlrev_b32_e32 v196, 5, v217
	v_or_b32_e32 v0, v196, v214
	v_ashrrev_i32_e32 v1, 31, v0
	v_bfe_u32 v213, v194, 5, 1
	v_lshlrev_b64 v[0:1], 8, v[0:1]
	v_lshl_add_u64 v[0:1], s[34:35], 0, v[0:1]
	v_lshlrev_b32_e32 v198, 4, v213
	v_lshl_add_u64 v[0:1], v[0:1], 0, v[198:199]
	v_lshl_add_u64 v[2:3], v[0:1], 0, s[20:21]
	v_add_co_u32_e32 v0, vcc, s77, v0
	v_ashrrev_i32_e32 v215, 6, v194
	s_add_u32 s36, s36, 0x410000
	v_addc_co_u32_e32 v1, vcc, 0, v1, vcc
	v_readfirstlane_b32 s2, v215
	s_addc_u32 s37, s37, 0
	global_load_dwordx4 v[184:187], v[2:3], off offset:32
	global_load_dwordx4 v[180:183], v[2:3], off offset:64
	global_load_dwordx4 v[176:179], v[2:3], off offset:96
	global_load_dwordx4 v[172:175], v[2:3], off offset:128
	global_load_dwordx4 v[168:171], v[2:3], off offset:160
	global_load_dwordx4 v[164:167], v[2:3], off offset:192
	global_load_dwordx4 v[188:191], v[0:1], off
	global_load_dwordx4 v[160:163], v[2:3], off offset:224
	v_bfe_u32 v199, v194, 4, 2
	v_bfe_u32 v0, v194, 2, 2
	v_lshrrev_b32_e32 v1, 1, v194
	s_lshl_b32 s3, s2, 2
	s_lshl_b32 s34, s2, 1
	v_and_or_b32 v6, v1, 8, v0
	v_or_b32_e32 v0, s3, v199
	s_and_b32 s3, s3, -16
	s_and_b32 s35, s34, 4
	s_or_b32 s3, s3, s35
	v_or_b32_e32 v2, s3, v6
	s_add_i32 s3, s2, 8
	v_and_b32_e32 v4, 63, v194
	v_and_or_b32 v14, s34, 2, v213
	s_lshl_b32 s34, s3, 2
	s_lshl_b32 s35, s3, 1
	v_lshlrev_b32_e32 v8, 3, v4
	v_lshlrev_b32_e32 v197, 4, v4
	v_or_b32_e32 v4, s34, v199
	s_and_b32 s34, s34, -16
	s_and_b32 s41, s35, 4
	v_lshlrev_b32_e32 v9, 1, v194
	v_and_b32_e32 v211, 15, v194
	v_ashrrev_i32_e32 v1, 31, v0
	s_or_b32 s34, s34, s41
	v_and_b32_e32 v12, 0x100, v8
	v_bitop3_b32 v10, v0, v211, 7 bitop3:0x6c
	v_ashrrev_i32_e32 v5, 31, v4
	v_bitop3_b32 v15, v4, v211, 7 bitop3:0x6c
	v_or_b32_e32 v6, s34, v6
	v_and_b32_e32 v17, 24, v8
	v_and_b32_e32 v19, 32, v9
	v_lshlrev_b64 v[8:9], 8, v[0:1]
	s_lshl_b32 s34, s2, 10
	v_lshlrev_b32_e32 v212, 3, v194
	v_and_or_b32 v16, s35, 2, v213
	v_lshl_or_b32 v8, v10, 4, v8
	s_add_i32 s35, s34, 0
	v_lshlrev_b64 v[4:5], 8, v[4:5]
	v_lshlrev_b32_e32 v15, 4, v15
	v_lshrrev_b32_e32 v132, 1, v194
	v_and_b32_e32 v132, 0x80, v132
	v_xor_b32_e32 v8, v8, v132
	v_xor_b32_e32 v15, v15, v132
	v_and_b32_e32 v13, 24, v212
	v_ashrrev_i32_e32 v3, 31, v2
	v_lshl_add_u64 v[10:11], s[36:37], 0, v[8:9]
	s_mov_b32 m0, s35
	v_or_b32_e32 v4, v4, v15
	v_ashrrev_i32_e32 v7, 31, v6
	global_load_lds_dwordx4 v[10:11], off
	v_lshl_add_u64 v[128:129], v[10:11], 0, s[18:19]
	v_lshl_add_u64 v[4:5], s[36:37], 0, v[4:5]
	v_lshl_add_u64 v[130:131], v[4:5], 0, s[18:19]
	s_add_i32 m0, s35, 0x2000
	v_lshlrev_b32_e32 v1, 6, v14
	v_lshlrev_b32_e32 v10, 1, v13
	v_lshlrev_b64 v[2:3], 9, v[2:3]
	global_load_lds_dwordx4 v[4:5], off
	s_add_i32 m0, s35, 0x4000
	s_nop 0
	global_load_lds_dwordx4 v[128:129], off
	s_add_i32 m0, s35, 0x6000
	s_nop 0
	global_load_lds_dwordx4 v[130:131], off
	v_or3_b32 v4, v1, v10, v2
	v_lshrrev_b32_e32 v132, 11, v4
	v_lshrrev_b32_e32 v133, 12, v4
	v_xor_b32_e32 v132, v132, v133
	v_and_b32_e32 v132, 1, v132
	v_mul_u32_u24_e32 v132, 0x1800, v132
	v_xor_b32_e32 v4, v4, v132
	v_mov_b32_e32 v5, v3
	v_lshlrev_b32_e32 v1, 6, v16
	v_lshlrev_b64 v[6:7], 9, v[6:7]
	v_lshl_add_u64 v[4:5], s[30:31], 0, v[4:5]
	s_add_i32 m0, s35, 0x8000
	v_or3_b32 v10, v1, v10, v6
	v_lshrrev_b32_e32 v132, 11, v10
	v_lshrrev_b32_e32 v133, 12, v10
	v_xor_b32_e32 v132, v132, v133
	v_and_b32_e32 v132, 1, v132
	v_mul_u32_u24_e32 v132, 0x1800, v132
	v_xor_b32_e32 v10, v10, v132
	v_mov_b32_e32 v11, v7
	global_load_lds_dwordx4 v[4:5], off
	v_lshl_add_u64 v[10:11], s[30:31], 0, v[10:11]
	s_add_i32 m0, s35, 0xa000
	v_lshl_add_u64 v[4:5], v[4:5], 0, s[10:11]
	global_load_lds_dwordx4 v[10:11], off
	s_add_i32 m0, s35, 0xc000
	v_and_b32_e32 v216, 1, v215
	global_load_lds_dwordx4 v[4:5], off
	v_lshl_add_u64 v[4:5], v[10:11], 0, s[10:11]
	s_add_i32 m0, s35, 0xe000
	v_lshlrev_b32_e32 v20, 13, v216
	global_load_lds_dwordx4 v[4:5], off
	s_cmp_lg_u32 s33, -1
	v_lshl_or_b32 v1, v214, 8, v20
	s_cselect_b32 s30, s33, 0
	s_and_b32 s2, s2, 1
	v_lshlrev_b32_e32 v4, 4, v194
	v_add_u32_e32 v220, 0, v1
	s_lshl_b32 s2, s2, 6
	v_and_b32_e32 v1, 32, v194
	v_and_b32_e32 v5, 0x70, v4
	v_bitop3_b32 v229, v198, v4, s58 bitop3:0x78
	v_or3_b32 v4, s2, v1, v13
	s_and_b32 s2, s3, 1
	s_lshl_b32 s2, s2, 6
	v_or3_b32 v1, s2, v1, v13
	v_add_u32_e32 v0, 32, v0
	v_and_b32_e32 v18, 0xc0, v197
	s_waitcnt vmcnt(0)
	v_lshl_or_b32 v6, v1, 1, v6
	v_ashrrev_i32_e32 v1, 31, v0
	s_waitcnt lgkmcnt(0)
	s_barrier
; __device__ __forceinline__ int v_rd_base(int lane) { return ((lane & 3) << 3) | (((lane >> 2) & 3) << 6) | (((lane >> 4) & 1) << 5) | (((lane >> 5) & 1) << 8); }
; #define RAWBAR() do { asm volatile("s_waitcnt lgkmcnt(0)" ::: "memory"); __builtin_amdgcn_s_barrier(); asm volatile("" ::: "memory"); } while (0)
; #define RAWBAR() do { asm volatile("s_waitcnt lgkmcnt(0)" ::: "memory"); __builtin_amdgcn_s_barrier(); asm volatile("" ::: "memory"); } while (0)
; #define RAWBAR() do { asm volatile("s_waitcnt lgkmcnt(0)" ::: "memory"); __builtin_amdgcn_s_barrier(); asm volatile("" ::: "memory"); } while (0)
; template <int MODE> ...
;     ...
;   f32x16 o[8] = {}; bf16x8 qr[8]; float lsum = 0.f;
;   const bf16* Qw = Qb + (long)(g * 32 + r32) * 128 + hi * 8;
; #pragma unroll
;   for (int d0 = 0; d0 < 8; ++d0) qr[d0] = St::ld8(Qw + d0 * 16);
;   const int vb0 = (int)(uintptr_t)V_lds + v_rd_base(lane) + 2 * kh * 4096;
;   const int krow = 32 * kh + r32;
;   typedef __attribute__((address_space(3))) unsigned lds_u32;
;   const int wu = __builtin_amdgcn_readfirstlane(wid);
;   long gk[2], gv[2];
; #pragma unroll
;   for (int c = 0; c < 2; ++c) { const int q = wu + 8 * c;
;     const int r = 4 * q + (lane >> 4), pch = lane & 15; gk[c] = (long)r * 128 + ((pch ^ (r & 7)) * 8);
;     const int st = 2 * q + (lane >> 5), kk = (st >> 2) * 8 + ((lane >> 2) & 7), k = (kk & ~0xC) | ((kk & 4) << 1) | ((kk & 8) >> 1), cc = (st & 3) * 32 + (lane & 3) * 8;
;     gv[c] = (long)k * 256 + cc; }
;     ...
;   const int NT = seq / KVBLK;
;   STAGE(0, 0); asm volatile("s_waitcnt vmcnt(0)" ::: "memory"); RAWBAR();
;   if (false) __builtin_amdgcn_s_setprio(1);
;   for (int j = 0; j < NT; ++j) {
;     const int buf = j & 1;
;     if (j + 1 < NT) { STAGE((j + 1) * KVBLK, buf ^ 1); }
;     const char* Kb = K_lds + buf * 16384;
;     f32x16 pe = {}, po = {};
; #pragma unroll
;     for (int d0 = 0; d0 < 8; d0 += 2) {
;       const bf16x8 k0 = *reinterpret_cast<const bf16x8*>(Kb + KSWZ(krow, (d0 * 16 + hi * 8) * 2));
;       const bf16x8 k1 = *reinterpret_cast<const bf16x8*>(Kb + KSWZ(krow, ((d0 + 1) * 16 + hi * 8) * 2));
;       pe = __builtin_amdgcn_mfma_f32_32x32x16_bf16(k0, qr[d0], pe, 0, 0, 0);
;       po = __builtin_amdgcn_mfma_f32_32x32x16_bf16(k1, qr[d0 + 1], po, 0, 0, 0); }
	v_add_u32_e32 v10, s30, v18
	v_readlane_b32 s84, v251, 28
	v_lshlrev_b64 v[0:1], 8, v[0:1]
	v_add3_u32 v10, v10, v17, v19
	v_lshl_or_b32 v2, v4, 1, v2
	v_readlane_b32 s85, v251, 29
	v_or_b32_e32 v0, v0, v15
	v_mov_b32_e32 v219, 0
	s_mov_b32 s40, 0
	v_add3_u32 v218, v10, v12, v20
	v_bitop3_b32 v228, v198, v5, 32 bitop3:0x36
	v_bitop3_b32 v227, v198, v5, 64 bitop3:0x36
	v_bitop3_b32 v226, v198, v5, s43 bitop3:0x36
	v_bitop3_b32 v225, v198, v5, s59 bitop3:0x36
	v_bitop3_b32 v223, v198, v5, s60 bitop3:0x36
	v_bitop3_b32 v222, v198, v5, s56 bitop3:0x36
	v_bitop3_b32 v221, v198, v5, s61 bitop3:0x36
	v_lshl_add_u64 v[200:201], s[84:85], 0, v[2:3]
	v_lshl_add_u64 v[202:203], s[84:85], 0, v[6:7]
	v_lshl_add_u64 v[204:205], s[8:9], 0, v[8:9]
	v_lshl_add_u64 v[206:207], s[8:9], 0, v[0:1]
	v_mov_b32_e32 v0, 0
	v_mov_b32_e32 v1, v219
	v_mov_b32_e32 v2, v219
	v_mov_b32_e32 v3, v219
	v_mov_b32_e32 v4, v219
	v_mov_b32_e32 v5, v219
	v_mov_b32_e32 v6, v219
	v_mov_b32_e32 v7, v219
	v_mov_b32_e32 v8, v219
	v_mov_b32_e32 v9, v219
	v_mov_b32_e32 v10, v219
	v_mov_b32_e32 v11, v219
	v_mov_b32_e32 v12, v219
	v_mov_b32_e32 v13, v219
	v_mov_b32_e32 v14, v219
	v_mov_b32_e32 v15, v219
	v_mov_b32_e32 v48, 0
	v_mov_b32_e32 v49, v219
	v_mov_b32_e32 v50, v219
	v_mov_b32_e32 v51, v219
	v_mov_b32_e32 v52, v219
	v_mov_b32_e32 v53, v219
	v_mov_b32_e32 v54, v219
	v_mov_b32_e32 v55, v219
	v_mov_b32_e32 v56, v219
	v_mov_b32_e32 v57, v219
	v_mov_b32_e32 v58, v219
	v_mov_b32_e32 v59, v219
	v_mov_b32_e32 v60, v219
	v_mov_b32_e32 v61, v219
	v_mov_b32_e32 v62, v219
	v_mov_b32_e32 v63, v219
	v_mov_b32_e32 v16, 0
	v_mov_b32_e32 v17, v219
	v_mov_b32_e32 v18, v219
	v_mov_b32_e32 v19, v219
	v_mov_b32_e32 v20, v219
	v_mov_b32_e32 v21, v219
	v_mov_b32_e32 v22, v219
	v_mov_b32_e32 v23, v219
	v_mov_b32_e32 v24, v219
	v_mov_b32_e32 v25, v219
	v_mov_b32_e32 v26, v219
	v_mov_b32_e32 v27, v219
	v_mov_b32_e32 v28, v219
	v_mov_b32_e32 v29, v219
	v_mov_b32_e32 v30, v219
	v_mov_b32_e32 v31, v219
	v_mov_b32_e32 v32, 0
	v_mov_b32_e32 v33, v219
	v_mov_b32_e32 v34, v219
	v_mov_b32_e32 v35, v219
	v_mov_b32_e32 v36, v219
	v_mov_b32_e32 v37, v219
	v_mov_b32_e32 v38, v219
	v_mov_b32_e32 v39, v219
	v_mov_b32_e32 v40, v219
	v_mov_b32_e32 v41, v219
	v_mov_b32_e32 v42, v219
	v_mov_b32_e32 v43, v219
	v_mov_b32_e32 v44, v219
	v_mov_b32_e32 v45, v219
	v_mov_b32_e32 v46, v219
	v_mov_b32_e32 v47, v219
	v_mov_b32_e32 v64, 0
	v_mov_b32_e32 v65, v219
	v_mov_b32_e32 v66, v219
	v_mov_b32_e32 v67, v219
	v_mov_b32_e32 v68, v219
	v_mov_b32_e32 v69, v219
	v_mov_b32_e32 v70, v219
	v_mov_b32_e32 v71, v219
	v_mov_b32_e32 v72, v219
	v_mov_b32_e32 v73, v219
	v_mov_b32_e32 v74, v219
	v_mov_b32_e32 v75, v219
	v_mov_b32_e32 v76, v219
	v_mov_b32_e32 v77, v219
	v_mov_b32_e32 v78, v219
	v_mov_b32_e32 v79, v219
	v_mov_b32_e32 v80, 0
	v_mov_b32_e32 v81, v219
	v_mov_b32_e32 v82, v219
	v_mov_b32_e32 v83, v219
	v_mov_b32_e32 v84, v219
	v_mov_b32_e32 v85, v219
	v_mov_b32_e32 v86, v219
	v_mov_b32_e32 v87, v219
	v_mov_b32_e32 v88, v219
	v_mov_b32_e32 v89, v219
	v_mov_b32_e32 v90, v219
	v_mov_b32_e32 v91, v219
	v_mov_b32_e32 v92, v219
	v_mov_b32_e32 v93, v219
	v_mov_b32_e32 v94, v219
	v_mov_b32_e32 v95, v219
	v_mov_b32_e32 v96, 0
	v_mov_b32_e32 v97, v219
	v_mov_b32_e32 v98, v219
	v_mov_b32_e32 v99, v219
	v_mov_b32_e32 v100, v219
	v_mov_b32_e32 v101, v219
	v_mov_b32_e32 v102, v219
	v_mov_b32_e32 v103, v219
	v_mov_b32_e32 v104, v219
	v_mov_b32_e32 v105, v219
	v_mov_b32_e32 v106, v219
	v_mov_b32_e32 v107, v219
	v_mov_b32_e32 v108, v219
	v_mov_b32_e32 v109, v219
	v_mov_b32_e32 v110, v219
	v_mov_b32_e32 v111, v219
	v_mov_b32_e32 v112, 0
	v_mov_b32_e32 v113, v219
	v_mov_b32_e32 v114, v219
	v_mov_b32_e32 v115, v219
	v_mov_b32_e32 v116, v219
	v_mov_b32_e32 v117, v219
	v_mov_b32_e32 v118, v219
	v_mov_b32_e32 v119, v219
	v_mov_b32_e32 v120, v219
	v_mov_b32_e32 v121, v219
	v_mov_b32_e32 v122, v219
	v_mov_b32_e32 v123, v219
	v_mov_b32_e32 v124, v219
	v_mov_b32_e32 v125, v219
	v_mov_b32_e32 v126, v219
	v_mov_b32_e32 v127, v219
	v_readlane_b32 s86, v251, 30
	v_readlane_b32 s87, v251, 31
	s_waitcnt vmcnt(0)
	v_subrev_u32_e32 v225, s8, v204
	v_subrev_u32_e32 v223, s8, v206
	v_subrev_u32_e32 v222, s84, v200
	v_subrev_u32_e32 v221, s84, v202
	v_lshrrev_b32_e32 v246, 11, v222
	v_lshrrev_b32_e32 v247, 12, v222
	v_xor_b32_e32 v246, v246, v247
	v_and_b32_e32 v246, 1, v246
	v_mul_u32_u24_e32 v246, 0x1800, v246
	v_xor_b32_e32 v222, v222, v246
	v_lshrrev_b32_e32 v246, 11, v221
	v_lshrrev_b32_e32 v247, 12, v221
	v_xor_b32_e32 v246, v246, v247
	v_and_b32_e32 v246, 1, v246
	v_mul_u32_u24_e32 v246, 0x1800, v246
	v_xor_b32_e32 v221, v221, v246
	v_add_u32_e32 v246, 0x100, v222
	v_add_u32_e32 v247, 0x100, v221
	s_add_u32 s86, s8, s26
	s_addc_u32 s87, s9, s27
	s_add_u32 s86, s86, 0x4000
	s_addc_u32 s87, s87, 0
	s_add_u32 s2, s84, s26
	s_addc_u32 s3, s85, s27
	s_add_u32 s2, s2, s12
	s_addc_u32 s3, s3, s13
	v_add_u32_e32 v229, v220, v229
	v_add_u32_e32 v228, v220, v228
	v_add_u32_e32 v227, v220, v227
	v_add_u32_e32 v226, v220, v226
	v_and_b32_e32 v204, 16, v194
	v_lshlrev_b32_e32 v204, 3, v204
	v_add_u32_e32 v226, v226, v204
	v_xor_b32_e32 v207, 0x80, v226
	v_add_u32_e32 v227, v227, v204
	v_xor_b32_e32 v206, 0x80, v227
	v_add_u32_e32 v228, v228, v204
	v_xor_b32_e32 v205, 0x80, v228
	v_add_u32_e32 v229, v229, v204
	v_xor_b32_e32 v204, 0x80, v229
	ds_read_b128 v[230:233], v229
	ds_read_b128 v[234:237], v228
	s_waitcnt lgkmcnt(0)
	v_mfma_f32_32x32x16_bf16 v[144:159], v[230:233], v[188:191], 0
	v_mfma_f32_32x32x16_bf16 v[144:159], v[234:237], v[184:187], v[144:159]
	ds_read_b128 v[230:233], v227
	ds_read_b128 v[234:237], v226
	s_waitcnt lgkmcnt(0)
	v_mfma_f32_32x32x16_bf16 v[144:159], v[230:233], v[180:183], v[144:159]
	v_mfma_f32_32x32x16_bf16 v[144:159], v[234:237], v[176:179], v[144:159]
	ds_read_b128 v[230:233], v204
	ds_read_b128 v[234:237], v205
	s_waitcnt lgkmcnt(0)
	v_mfma_f32_32x32x16_bf16 v[144:159], v[230:233], v[172:175], v[144:159]
	v_mfma_f32_32x32x16_bf16 v[144:159], v[234:237], v[168:171], v[144:159]
	ds_read_b128 v[230:233], v206
	ds_read_b128 v[234:237], v207
	s_waitcnt lgkmcnt(0)
	v_mfma_f32_32x32x16_bf16 v[144:159], v[230:233], v[164:167], v[144:159]
	v_mfma_f32_32x32x16_bf16 v[144:159], v[234:237], v[160:163], v[144:159]
	s_mov_b32 s84, 0
	s_barrier
	s_cmp_lt_u32 s34, 0x1000
	s_cbranch_scc0 .LattnBpre_m1
; #define SBAR() __builtin_amdgcn_sched_barrier(0)
; #define PVR(S, DA, DB, vbase) do { S[0] = tr_read<v_rd_off(DA, 0, 0)>(vbase); S[1] = tr_read<v_rd_off(DA, 0, 1)>(vbase); S[2] = tr_read<v_rd_off(DB, 0, 0)>(vbase); S[3] = tr_read<v_rd_off(DB, 0, 1)>(vbase); \
;     S[4] = tr_read<v_rd_off(DA, 1, 0)>(vbase); S[5] = tr_read<v_rd_off(DA, 1, 1)>(vbase); S[6] = tr_read<v_rd_off(DB, 1, 0)>(vbase); S[7] = tr_read<v_rd_off(DB, 1, 1)>(vbase); } while (0)
; #define RAWBAR() do { asm volatile("s_waitcnt lgkmcnt(0)" ::: "memory"); __builtin_amdgcn_s_barrier(); asm volatile("" ::: "memory"); } while (0)
; #define RAWBAR() do { asm volatile("s_waitcnt lgkmcnt(0)" ::: "memory"); __builtin_amdgcn_s_barrier(); asm volatile("" ::: "memory"); } while (0)
; #define RAWBAR() do { asm volatile("s_waitcnt lgkmcnt(0)" ::: "memory"); __builtin_amdgcn_s_barrier(); asm volatile("" ::: "memory"); } while (0)
; #define RAWBAR() do { asm volatile("s_waitcnt lgkmcnt(0)" ::: "memory"); __builtin_amdgcn_s_barrier(); asm volatile("" ::: "memory"); } while (0)
; #define RAWBAR() do { asm volatile("s_waitcnt lgkmcnt(0)" ::: "memory"); __builtin_amdgcn_s_barrier(); asm volatile("" ::: "memory"); } while (0)
; template <int MODE> ...
;     ...
;     if (j + 1 < NT) { STAGE((j + 1) * KVBLK, buf ^ 1); }
;     const char* Kb = K_lds + buf * 16384;
;     f32x16 pe = {}, po = {};
; #pragma unroll
;     for (int d0 = 0; d0 < 8; d0 += 2) {
;       const bf16x8 k0 = *reinterpret_cast<const bf16x8*>(Kb + KSWZ(krow, (d0 * 16 + hi * 8) * 2));
;       const bf16x8 k1 = *reinterpret_cast<const bf16x8*>(Kb + KSWZ(krow, ((d0 + 1) * 16 + hi * 8) * 2));
;       pe = __builtin_amdgcn_mfma_f32_32x32x16_bf16(k0, qr[d0], pe, 0, 0, 0);
;       po = __builtin_amdgcn_mfma_f32_32x32x16_bf16(k1, qr[d0 + 1], po, 0, 0, 0); }
;     const int vo = vb0 + buf * 32768;
;     s16x4 R0_[8], R1_[8];
;     PVR(R0_, 0, 1, vo);
;     f32x16 p;
; #pragma unroll
;     for (int r = 0; r < 16; ++r) p[r] = __builtin_amdgcn_exp2f(fmaf(pe[r] + po[r], C, negMc));
;     float ps = 0.f;
; #pragma unroll
;     for (int r = 0; r < 16; ++r) ps += p[r];
;     lsum += ps;
;     const bf16x8 own0 = pk8(p, 0), own1 = pk8(p, 8);
;     SBAR();
;     PV_TAIL4(o, vo, vo + 16384, own0, own1);
;     asm volatile("s_waitcnt vmcnt(0)" ::: "memory");
;     RAWBAR();
.LBB0_1023:
	ds_read_b128 v[230:233], v229 offset:16384
	ds_read_b128 v[234:237], v228 offset:16384
	ds_read_b128 v[238:241], v227 offset:16384
	ds_read_b128 v[242:245], v226 offset:16384
	s_mov_b32 m0, s34
	s_nop 0
	global_load_lds_dwordx4 v225, s[86:87] sc1
	s_add_i32 m0, s34, 0x2000
	s_nop 0
	global_load_lds_dwordx4 v223, s[86:87] sc1
	v_exp_f32_e32 v144, v144
	v_exp_f32_e32 v145, v145
	v_exp_f32_e32 v146, v146
	v_exp_f32_e32 v147, v147
	s_waitcnt lgkmcnt(2)
	v_mfma_f32_32x32x16_bf16 v[128:143], v[230:233], v[188:191], 0
	v_mfma_f32_32x32x16_bf16 v[128:143], v[234:237], v[184:187], v[128:143]
	ds_read_b128 v[230:233], v204 offset:16384
	ds_read_b128 v[234:237], v205 offset:16384
	v_exp_f32_e32 v148, v148
	v_exp_f32_e32 v149, v149
	v_exp_f32_e32 v150, v150
	v_exp_f32_e32 v151, v151
	v_add_f32_e32 v250, v144, v145
	v_add_f32_e32 v250, v146, v250
	v_add_f32_e32 v250, v147, v250
	s_waitcnt lgkmcnt(2)
	v_mfma_f32_32x32x16_bf16 v[128:143], v[238:241], v[180:183], v[128:143]
	v_mfma_f32_32x32x16_bf16 v[128:143], v[242:245], v[176:179], v[128:143]
	ds_read_b128 v[238:241], v206 offset:16384
	ds_read_b128 v[242:245], v207 offset:16384
	v_exp_f32_e32 v152, v152
	v_exp_f32_e32 v153, v153
	v_exp_f32_e32 v154, v154
	v_exp_f32_e32 v155, v155
	v_add_f32_e32 v250, v148, v250
	v_add_f32_e32 v250, v149, v250
	v_add_f32_e32 v250, v150, v250
	v_add_f32_e32 v250, v151, v250
	s_waitcnt lgkmcnt(2)
	v_mfma_f32_32x32x16_bf16 v[128:143], v[230:233], v[172:175], v[128:143]
	v_mfma_f32_32x32x16_bf16 v[128:143], v[234:237], v[168:171], v[128:143]
	v_exp_f32_e32 v156, v156
	v_exp_f32_e32 v157, v157
	v_exp_f32_e32 v158, v158
	v_exp_f32_e32 v159, v159
	v_add_f32_e32 v250, v152, v250
	v_add_f32_e32 v250, v153, v250
	v_add_f32_e32 v250, v154, v250
	v_add_f32_e32 v250, v155, v250
	v_cvt_pk_bf16_f32 v230, v144, v145
	v_cvt_pk_bf16_f32 v231, v146, v147
	v_cvt_pk_bf16_f32 v232, v148, v149
	v_cvt_pk_bf16_f32 v233, v150, v151
	s_waitcnt lgkmcnt(0)
	v_mfma_f32_32x32x16_bf16 v[128:143], v[238:241], v[164:167], v[128:143]
	v_mfma_f32_32x32x16_bf16 v[128:143], v[242:245], v[160:163], v[128:143]
	v_add_u32_e32 v249, s84, v218
	s_add_i32 s85, s84, 0x8000
	s_cmp_eq_u32 s85, 0x18000
	s_cselect_b32 s85, 0, s85
	ds_read_b64_tr_b16 v[238:239], v249 offset:0
	ds_read_b64_tr_b16 v[240:241], v249 offset:2048
	ds_read_b64_tr_b16 v[242:243], v249 offset:512
	ds_read_b64_tr_b16 v[244:245], v249 offset:2560
	ds_read_b64_tr_b16 v[144:145], v249 offset:4096
	ds_read_b64_tr_b16 v[146:147], v249 offset:6144
	ds_read_b64_tr_b16 v[148:149], v249 offset:4608
	ds_read_b64_tr_b16 v[150:151], v249 offset:6656
	v_add_f32_e32 v250, v156, v250
	v_add_f32_e32 v250, v157, v250
	v_add_f32_e32 v250, v158, v250
	v_add_f32_e32 v250, v159, v250
	v_cvt_pk_bf16_f32 v234, v152, v153
	v_cvt_pk_bf16_f32 v235, v154, v155
	v_cvt_pk_bf16_f32 v236, v156, v157
	v_cvt_pk_bf16_f32 v237, v158, v159
	v_add_f32_e32 v219, v219, v250
	ds_read_b64_tr_b16 v[152:153], v249 offset:1024
	ds_read_b64_tr_b16 v[154:155], v249 offset:3072
	ds_read_b64_tr_b16 v[156:157], v249 offset:1536
	ds_read_b64_tr_b16 v[158:159], v249 offset:3584
	s_waitcnt lgkmcnt(8)
	v_mfma_f32_32x32x16_bf16 v[112:127], v[230:233], v[238:241], v[112:127]
	v_mfma_f32_32x32x16_bf16 v[96:111], v[230:233], v[242:245], v[96:111]
	ds_read_b64_tr_b16 v[238:239], v249 offset:5120
	ds_read_b64_tr_b16 v[240:241], v249 offset:7168
	ds_read_b64_tr_b16 v[242:243], v249 offset:5632
	ds_read_b64_tr_b16 v[244:245], v249 offset:7680
	s_add_i32 s30, s85, s34
	s_add_i32 m0, s30, 0x8000
	s_nop 0
	global_load_lds_dwordx4 v222, s[2:3] sc1
	s_waitcnt lgkmcnt(8)
	v_mfma_f32_32x32x16_bf16 v[112:127], v[234:237], v[144:147], v[112:127]
	v_mfma_f32_32x32x16_bf16 v[96:111], v[234:237], v[148:151], v[96:111]
	ds_read_b64_tr_b16 v[144:145], v249 offset:16384
	ds_read_b64_tr_b16 v[146:147], v249 offset:18432
	ds_read_b64_tr_b16 v[148:149], v249 offset:16896
	ds_read_b64_tr_b16 v[150:151], v249 offset:18944
	s_add_i32 s30, s85, s34
	s_add_i32 m0, s30, 0xa000
	s_nop 0
	global_load_lds_dwordx4 v221, s[2:3] sc1
	s_waitcnt lgkmcnt(8)
	v_mfma_f32_32x32x16_bf16 v[80:95], v[230:233], v[152:155], v[80:95]
	v_mfma_f32_32x32x16_bf16 v[64:79], v[230:233], v[156:159], v[64:79]
	ds_read_b64_tr_b16 v[152:153], v249 offset:20480
	ds_read_b64_tr_b16 v[154:155], v249 offset:22528
	ds_read_b64_tr_b16 v[156:157], v249 offset:20992
	ds_read_b64_tr_b16 v[158:159], v249 offset:23040
	s_add_i32 s30, s85, s34
	s_add_i32 m0, s30, 0xc000
	s_nop 0
	global_load_lds_dwordx4 v246, s[2:3] sc1
	s_waitcnt lgkmcnt(8)
	v_mfma_f32_32x32x16_bf16 v[80:95], v[234:237], v[238:241], v[80:95]
	v_mfma_f32_32x32x16_bf16 v[64:79], v[234:237], v[242:245], v[64:79]
	ds_read_b64_tr_b16 v[238:239], v249 offset:17408
	ds_read_b64_tr_b16 v[240:241], v249 offset:19456
	ds_read_b64_tr_b16 v[242:243], v249 offset:17920
	ds_read_b64_tr_b16 v[244:245], v249 offset:19968
	s_add_i32 s30, s85, s34
	s_add_i32 m0, s30, 0xe000
	s_nop 0
	global_load_lds_dwordx4 v247, s[2:3] sc1
	s_waitcnt lgkmcnt(8)
	v_mfma_f32_32x32x16_bf16 v[32:47], v[230:233], v[144:147], v[32:47]
	v_mfma_f32_32x32x16_bf16 v[16:31], v[230:233], v[148:151], v[16:31]
	ds_read_b64_tr_b16 v[144:145], v249 offset:21504
	ds_read_b64_tr_b16 v[146:147], v249 offset:23552
	ds_read_b64_tr_b16 v[148:149], v249 offset:22016
	ds_read_b64_tr_b16 v[150:151], v249 offset:24064
	s_waitcnt lgkmcnt(8)
	v_mfma_f32_32x32x16_bf16 v[32:47], v[234:237], v[152:155], v[32:47]
	v_mfma_f32_32x32x16_bf16 v[16:31], v[234:237], v[156:159], v[16:31]
	s_waitcnt lgkmcnt(0)
	v_mfma_f32_32x32x16_bf16 v[48:63], v[230:233], v[238:241], v[48:63]
	s_waitcnt vmcnt(0)
	s_barrier
; #define SBAR() __builtin_amdgcn_sched_barrier(0)
; #define PVR(S, DA, DB, vbase) do { S[0] = tr_read<v_rd_off(DA, 0, 0)>(vbase); S[1] = tr_read<v_rd_off(DA, 0, 1)>(vbase); S[2] = tr_read<v_rd_off(DB, 0, 0)>(vbase); S[3] = tr_read<v_rd_off(DB, 0, 1)>(vbase); \
;     S[4] = tr_read<v_rd_off(DA, 1, 0)>(vbase); S[5] = tr_read<v_rd_off(DA, 1, 1)>(vbase); S[6] = tr_read<v_rd_off(DB, 1, 0)>(vbase); S[7] = tr_read<v_rd_off(DB, 1, 1)>(vbase); } while (0)
; #define RAWBAR() do { asm volatile("s_waitcnt lgkmcnt(0)" ::: "memory"); __builtin_amdgcn_s_barrier(); asm volatile("" ::: "memory"); } while (0)
; #define RAWBAR() do { asm volatile("s_waitcnt lgkmcnt(0)" ::: "memory"); __builtin_amdgcn_s_barrier(); asm volatile("" ::: "memory"); } while (0)
; #define RAWBAR() do { asm volatile("s_waitcnt lgkmcnt(0)" ::: "memory"); __builtin_amdgcn_s_barrier(); asm volatile("" ::: "memory"); } while (0)
; #define RAWBAR() do { asm volatile("s_waitcnt lgkmcnt(0)" ::: "memory"); __builtin_amdgcn_s_barrier(); asm volatile("" ::: "memory"); } while (0)
; #define RAWBAR() do { asm volatile("s_waitcnt lgkmcnt(0)" ::: "memory"); __builtin_amdgcn_s_barrier(); asm volatile("" ::: "memory"); } while (0)
; template <int MODE> ...
;     ...
;   for (int j = 0; j < NT; ++j) {
;     const int buf = j & 1;
;     if (j + 1 < NT) { STAGE((j + 1) * KVBLK, buf ^ 1); }
;     const char* Kb = K_lds + buf * 16384;
;     f32x16 pe = {}, po = {};
; #pragma unroll
;     for (int d0 = 0; d0 < 8; d0 += 2) {
;       const bf16x8 k0 = *reinterpret_cast<const bf16x8*>(Kb + KSWZ(krow, (d0 * 16 + hi * 8) * 2));
;       const bf16x8 k1 = *reinterpret_cast<const bf16x8*>(Kb + KSWZ(krow, ((d0 + 1) * 16 + hi * 8) * 2));
;       pe = __builtin_amdgcn_mfma_f32_32x32x16_bf16(k0, qr[d0], pe, 0, 0, 0);
;       po = __builtin_amdgcn_mfma_f32_32x32x16_bf16(k1, qr[d0 + 1], po, 0, 0, 0); }
;     const int vo = vb0 + buf * 32768;
;     s16x4 R0_[8], R1_[8];
;     PVR(R0_, 0, 1, vo);
;     f32x16 p;
; #pragma unroll
;     for (int r = 0; r < 16; ++r) p[r] = __builtin_amdgcn_exp2f(fmaf(pe[r] + po[r], C, negMc));
;     float ps = 0.f;
; #pragma unroll
;     for (int r = 0; r < 16; ++r) ps += p[r];
;     lsum += ps;
;     const bf16x8 own0 = pk8(p, 0), own1 = pk8(p, 8);
;     SBAR();
;     PV_TAIL4(o, vo, vo + 16384, own0, own1);
;     asm volatile("s_waitcnt vmcnt(0)" ::: "memory");
;     RAWBAR();
;   }
	s_add_u32 s86, s86, 0x4000
	s_addc_u32 s87, s87, 0
	s_add_u32 s2, s2, 0x8000
	s_addc_u32 s3, s3, 0
	v_mfma_f32_32x32x16_bf16 v[0:15], v[230:233], v[242:245], v[0:15]
	v_mfma_f32_32x32x16_bf16 v[48:63], v[234:237], v[144:147], v[48:63]
	v_mfma_f32_32x32x16_bf16 v[0:15], v[234:237], v[148:151], v[0:15]
	s_add_i32 s84, s84, 0x8000
	s_cmp_eq_u32 s84, 0x18000
	s_cselect_b32 s84, 0, s84
	ds_read_b128 v[230:233], v229 offset:0
	ds_read_b128 v[234:237], v228 offset:0
	ds_read_b128 v[238:241], v227 offset:0
	ds_read_b128 v[242:245], v226 offset:0
	s_add_i32 m0, s34, 0x4000
	s_nop 0
	global_load_lds_dwordx4 v225, s[86:87] sc1
	s_add_i32 m0, s34, 0x6000
	s_nop 0
	global_load_lds_dwordx4 v223, s[86:87] sc1
	v_exp_f32_e32 v128, v128
	v_exp_f32_e32 v129, v129
	v_exp_f32_e32 v130, v130
	v_exp_f32_e32 v131, v131
	s_waitcnt lgkmcnt(2)
	v_mfma_f32_32x32x16_bf16 v[144:159], v[230:233], v[188:191], 0
	v_mfma_f32_32x32x16_bf16 v[144:159], v[234:237], v[184:187], v[144:159]
	ds_read_b128 v[230:233], v204 offset:0
	ds_read_b128 v[234:237], v205 offset:0
	v_exp_f32_e32 v132, v132
	v_exp_f32_e32 v133, v133
	v_exp_f32_e32 v134, v134
	v_exp_f32_e32 v135, v135
	v_add_f32_e32 v250, v128, v129
	v_add_f32_e32 v250, v130, v250
	v_add_f32_e32 v250, v131, v250
	s_waitcnt lgkmcnt(2)
	v_mfma_f32_32x32x16_bf16 v[144:159], v[238:241], v[180:183], v[144:159]
	v_mfma_f32_32x32x16_bf16 v[144:159], v[242:245], v[176:179], v[144:159]
	ds_read_b128 v[238:241], v206 offset:0
	ds_read_b128 v[242:245], v207 offset:0
	v_exp_f32_e32 v136, v136
	v_exp_f32_e32 v137, v137
	v_exp_f32_e32 v138, v138
	v_exp_f32_e32 v139, v139
	v_add_f32_e32 v250, v132, v250
	v_add_f32_e32 v250, v133, v250
	v_add_f32_e32 v250, v134, v250
	v_add_f32_e32 v250, v135, v250
	s_waitcnt lgkmcnt(2)
	v_mfma_f32_32x32x16_bf16 v[144:159], v[230:233], v[172:175], v[144:159]
	v_mfma_f32_32x32x16_bf16 v[144:159], v[234:237], v[168:171], v[144:159]
	v_exp_f32_e32 v140, v140
	v_exp_f32_e32 v141, v141
	v_exp_f32_e32 v142, v142
	v_exp_f32_e32 v143, v143
	v_add_f32_e32 v250, v136, v250
	v_add_f32_e32 v250, v137, v250
	v_add_f32_e32 v250, v138, v250
	v_add_f32_e32 v250, v139, v250
	v_cvt_pk_bf16_f32 v230, v128, v129
	v_cvt_pk_bf16_f32 v231, v130, v131
	v_cvt_pk_bf16_f32 v232, v132, v133
	v_cvt_pk_bf16_f32 v233, v134, v135
	s_waitcnt lgkmcnt(0)
	v_mfma_f32_32x32x16_bf16 v[144:159], v[238:241], v[164:167], v[144:159]
	v_mfma_f32_32x32x16_bf16 v[144:159], v[242:245], v[160:163], v[144:159]
	v_add_u32_e32 v249, s84, v218
	s_add_i32 s85, s84, 0x8000
	s_cmp_eq_u32 s85, 0x18000
	s_cselect_b32 s85, 0, s85
	ds_read_b64_tr_b16 v[238:239], v249 offset:0
	ds_read_b64_tr_b16 v[240:241], v249 offset:2048
	ds_read_b64_tr_b16 v[242:243], v249 offset:512
	ds_read_b64_tr_b16 v[244:245], v249 offset:2560
	ds_read_b64_tr_b16 v[128:129], v249 offset:4096
	ds_read_b64_tr_b16 v[130:131], v249 offset:6144
	ds_read_b64_tr_b16 v[132:133], v249 offset:4608
	ds_read_b64_tr_b16 v[134:135], v249 offset:6656
	v_add_f32_e32 v250, v140, v250
	v_add_f32_e32 v250, v141, v250
	v_add_f32_e32 v250, v142, v250
	v_add_f32_e32 v250, v143, v250
	v_cvt_pk_bf16_f32 v234, v136, v137
	v_cvt_pk_bf16_f32 v235, v138, v139
	v_cvt_pk_bf16_f32 v236, v140, v141
	v_cvt_pk_bf16_f32 v237, v142, v143
	v_add_f32_e32 v219, v219, v250
	ds_read_b64_tr_b16 v[136:137], v249 offset:1024
	ds_read_b64_tr_b16 v[138:139], v249 offset:3072
	ds_read_b64_tr_b16 v[140:141], v249 offset:1536
	ds_read_b64_tr_b16 v[142:143], v249 offset:3584
	s_waitcnt lgkmcnt(8)
	v_mfma_f32_32x32x16_bf16 v[112:127], v[230:233], v[238:241], v[112:127]
	v_mfma_f32_32x32x16_bf16 v[96:111], v[230:233], v[242:245], v[96:111]
	ds_read_b64_tr_b16 v[238:239], v249 offset:5120
	ds_read_b64_tr_b16 v[240:241], v249 offset:7168
	ds_read_b64_tr_b16 v[242:243], v249 offset:5632
	ds_read_b64_tr_b16 v[244:245], v249 offset:7680
	s_add_i32 s30, s85, s34
	s_add_i32 m0, s30, 0x8000
	s_nop 0
	global_load_lds_dwordx4 v222, s[2:3] sc1
	s_waitcnt lgkmcnt(8)
	v_mfma_f32_32x32x16_bf16 v[112:127], v[234:237], v[128:131], v[112:127]
	v_mfma_f32_32x32x16_bf16 v[96:111], v[234:237], v[132:135], v[96:111]
	ds_read_b64_tr_b16 v[128:129], v249 offset:16384
	ds_read_b64_tr_b16 v[130:131], v249 offset:18432
	ds_read_b64_tr_b16 v[132:133], v249 offset:16896
	ds_read_b64_tr_b16 v[134:135], v249 offset:18944
	s_add_i32 s30, s85, s34
	s_add_i32 m0, s30, 0xa000
	s_nop 0
	global_load_lds_dwordx4 v221, s[2:3] sc1
	s_waitcnt lgkmcnt(8)
	v_mfma_f32_32x32x16_bf16 v[80:95], v[230:233], v[136:139], v[80:95]
	v_mfma_f32_32x32x16_bf16 v[64:79], v[230:233], v[140:143], v[64:79]
	ds_read_b64_tr_b16 v[136:137], v249 offset:20480
	ds_read_b64_tr_b16 v[138:139], v249 offset:22528
	ds_read_b64_tr_b16 v[140:141], v249 offset:20992
	ds_read_b64_tr_b16 v[142:143], v249 offset:23040
	s_add_i32 s30, s85, s34
	s_add_i32 m0, s30, 0xc000
	s_nop 0
	global_load_lds_dwordx4 v246, s[2:3] sc1
	s_waitcnt lgkmcnt(8)
	v_mfma_f32_32x32x16_bf16 v[80:95], v[234:237], v[238:241], v[80:95]
	v_mfma_f32_32x32x16_bf16 v[64:79], v[234:237], v[242:245], v[64:79]
	ds_read_b64_tr_b16 v[238:239], v249 offset:17408
	ds_read_b64_tr_b16 v[240:241], v249 offset:19456
	ds_read_b64_tr_b16 v[242:243], v249 offset:17920
	ds_read_b64_tr_b16 v[244:245], v249 offset:19968
	s_add_i32 s30, s85, s34
	s_add_i32 m0, s30, 0xe000
	s_nop 0
	global_load_lds_dwordx4 v247, s[2:3] sc1
	s_waitcnt lgkmcnt(8)
	v_mfma_f32_32x32x16_bf16 v[32:47], v[230:233], v[128:131], v[32:47]
	v_mfma_f32_32x32x16_bf16 v[16:31], v[230:233], v[132:135], v[16:31]
	ds_read_b64_tr_b16 v[128:129], v249 offset:21504
	ds_read_b64_tr_b16 v[130:131], v249 offset:23552
	ds_read_b64_tr_b16 v[132:133], v249 offset:22016
	ds_read_b64_tr_b16 v[134:135], v249 offset:24064
	s_waitcnt lgkmcnt(8)
	v_mfma_f32_32x32x16_bf16 v[32:47], v[234:237], v[136:139], v[32:47]
	v_mfma_f32_32x32x16_bf16 v[16:31], v[234:237], v[140:143], v[16:31]
	s_waitcnt lgkmcnt(0)
	v_mfma_f32_32x32x16_bf16 v[48:63], v[230:233], v[238:241], v[48:63]
	s_waitcnt vmcnt(0)
	s_barrier
	s_add_u32 s86, s86, 0x4000
	s_addc_u32 s87, s87, 0
	s_add_u32 s2, s2, 0x8000
	s_addc_u32 s3, s3, 0
	v_mfma_f32_32x32x16_bf16 v[0:15], v[230:233], v[242:245], v[0:15]
	v_mfma_f32_32x32x16_bf16 v[48:63], v[234:237], v[128:131], v[48:63]
	v_mfma_f32_32x32x16_bf16 v[0:15], v[234:237], v[132:135], v[0:15]
	s_add_i32 s84, s84, 0x8000
	s_cmp_eq_u32 s84, 0x18000
	s_cselect_b32 s84, 0, s84
	s_add_i32 s40, s40, 1
	s_cmpk_eq_i32 s40, 0x82
	s_cbranch_scc0 .LBB0_1023
	s_barrier
	s_branch .Lattn_join_m1

; #define SBAR() __builtin_amdgcn_sched_barrier(0)
; #define PVR(S, DA, DB, vbase) do { S[0] = tr_read<v_rd_off(DA, 0, 0)>(vbase); S[1] = tr_read<v_rd_off(DA, 0, 1)>(vbase); S[2] = tr_read<v_rd_off(DB, 0, 0)>(vbase); S[3] = tr_read<v_rd_off(DB, 0, 1)>(vbase); \
;     S[4] = tr_read<v_rd_off(DA, 1, 0)>(vbase); S[5] = tr_read<v_rd_off(DA, 1, 1)>(vbase); S[6] = tr_read<v_rd_off(DB, 1, 0)>(vbase); S[7] = tr_read<v_rd_off(DB, 1, 1)>(vbase); } while (0)
; #define RAWBAR() do { asm volatile("s_waitcnt lgkmcnt(0)" ::: "memory"); __builtin_amdgcn_s_barrier(); asm volatile("" ::: "memory"); } while (0)
; #define RAWBAR() do { asm volatile("s_waitcnt lgkmcnt(0)" ::: "memory"); __builtin_amdgcn_s_barrier(); asm volatile("" ::: "memory"); } while (0)
; #define RAWBAR() do { asm volatile("s_waitcnt lgkmcnt(0)" ::: "memory"); __builtin_amdgcn_s_barrier(); asm volatile("" ::: "memory"); } while (0)
; #define RAWBAR() do { asm volatile("s_waitcnt lgkmcnt(0)" ::: "memory"); __builtin_amdgcn_s_barrier(); asm volatile("" ::: "memory"); } while (0)
; #define RAWBAR() do { asm volatile("s_waitcnt lgkmcnt(0)" ::: "memory"); __builtin_amdgcn_s_barrier(); asm volatile("" ::: "memory"); } while (0)
; template <int MODE> ...
;     ...
;   for (int j = 0; j < NT; ++j) {
;     const int buf = j & 1;
;     if (j + 1 < NT) { STAGE((j + 1) * KVBLK, buf ^ 1); }
;     const char* Kb = K_lds + buf * 16384;
;     f32x16 pe = {}, po = {};
; #pragma unroll
;     for (int d0 = 0; d0 < 8; d0 += 2) {
;       const bf16x8 k0 = *reinterpret_cast<const bf16x8*>(Kb + KSWZ(krow, (d0 * 16 + hi * 8) * 2));
;       const bf16x8 k1 = *reinterpret_cast<const bf16x8*>(Kb + KSWZ(krow, ((d0 + 1) * 16 + hi * 8) * 2));
;       pe = __builtin_amdgcn_mfma_f32_32x32x16_bf16(k0, qr[d0], pe, 0, 0, 0);
;       po = __builtin_amdgcn_mfma_f32_32x32x16_bf16(k1, qr[d0 + 1], po, 0, 0, 0); }
;     const int vo = vb0 + buf * 32768;
;     s16x4 R0_[8], R1_[8];
;     PVR(R0_, 0, 1, vo);
;     f32x16 p;
; #pragma unroll
;     for (int r = 0; r < 16; ++r) p[r] = __builtin_amdgcn_exp2f(fmaf(pe[r] + po[r], C, negMc));
;     float ps = 0.f;
; #pragma unroll
;     for (int r = 0; r < 16; ++r) ps += p[r];
;     lsum += ps;
;     const bf16x8 own0 = pk8(p, 0), own1 = pk8(p, 8);
;     SBAR();
;     PV_TAIL4(o, vo, vo + 16384, own0, own1);
;     asm volatile("s_waitcnt vmcnt(0)" ::: "memory");
;     RAWBAR();
;   }
.LattnB_m1:
	ds_read_b128 v[230:233], v229 offset:16384
	ds_read_b128 v[234:237], v228 offset:16384
	ds_read_b128 v[238:241], v227 offset:16384
	ds_read_b128 v[242:245], v226 offset:16384
	v_exp_f32_e32 v144, v144
	v_exp_f32_e32 v145, v145
	v_exp_f32_e32 v146, v146
	v_exp_f32_e32 v147, v147
	s_waitcnt lgkmcnt(2)
	v_mfma_f32_32x32x16_bf16 v[128:143], v[230:233], v[188:191], 0
	v_mfma_f32_32x32x16_bf16 v[128:143], v[234:237], v[184:187], v[128:143]
	ds_read_b128 v[230:233], v204 offset:16384
	ds_read_b128 v[234:237], v205 offset:16384
	v_exp_f32_e32 v148, v148
	v_exp_f32_e32 v149, v149
	v_exp_f32_e32 v150, v150
	v_exp_f32_e32 v151, v151
	v_add_f32_e32 v250, v144, v145
	v_add_f32_e32 v250, v146, v250
	v_add_f32_e32 v250, v147, v250
	s_waitcnt lgkmcnt(2)
	v_mfma_f32_32x32x16_bf16 v[128:143], v[238:241], v[180:183], v[128:143]
	v_mfma_f32_32x32x16_bf16 v[128:143], v[242:245], v[176:179], v[128:143]
	ds_read_b128 v[238:241], v206 offset:16384
	ds_read_b128 v[242:245], v207 offset:16384
	v_exp_f32_e32 v152, v152
	v_exp_f32_e32 v153, v153
	v_exp_f32_e32 v154, v154
	v_exp_f32_e32 v155, v155
	v_add_f32_e32 v250, v148, v250
	v_add_f32_e32 v250, v149, v250
	v_add_f32_e32 v250, v150, v250
	v_add_f32_e32 v250, v151, v250
	s_waitcnt lgkmcnt(2)
	v_mfma_f32_32x32x16_bf16 v[128:143], v[230:233], v[172:175], v[128:143]
	v_mfma_f32_32x32x16_bf16 v[128:143], v[234:237], v[168:171], v[128:143]
	v_exp_f32_e32 v156, v156
	v_exp_f32_e32 v157, v157
	v_exp_f32_e32 v158, v158
	v_exp_f32_e32 v159, v159
	v_add_f32_e32 v250, v152, v250
	v_add_f32_e32 v250, v153, v250
	v_add_f32_e32 v250, v154, v250
	v_add_f32_e32 v250, v155, v250
	v_cvt_pk_bf16_f32 v230, v144, v145
	v_cvt_pk_bf16_f32 v231, v146, v147
	v_cvt_pk_bf16_f32 v232, v148, v149
	v_cvt_pk_bf16_f32 v233, v150, v151
	s_waitcnt lgkmcnt(0)
	v_mfma_f32_32x32x16_bf16 v[128:143], v[238:241], v[164:167], v[128:143]
	v_mfma_f32_32x32x16_bf16 v[128:143], v[242:245], v[160:163], v[128:143]
	s_waitcnt vmcnt(0)
	s_barrier
	s_add_u32 s86, s86, 0x4000
	s_addc_u32 s87, s87, 0
	s_add_u32 s2, s2, 0x8000
	s_addc_u32 s3, s3, 0
	s_add_i32 m0, s34, 0x4000
	s_nop 0
	global_load_lds_dwordx4 v225, s[86:87] sc1
	s_add_i32 m0, s34, 0x6000
	s_nop 0
	global_load_lds_dwordx4 v223, s[86:87] sc1
	v_add_u32_e32 v249, s84, v218
	s_sub_u32 s85, s84, 0x8000
	s_cmp_eq_u32 s84, 0
	s_cselect_b32 s85, 0x10000, s85
	ds_read_b64_tr_b16 v[238:239], v249 offset:0
	ds_read_b64_tr_b16 v[240:241], v249 offset:2048
	ds_read_b64_tr_b16 v[242:243], v249 offset:512
	ds_read_b64_tr_b16 v[244:245], v249 offset:2560
	ds_read_b64_tr_b16 v[144:145], v249 offset:4096
	ds_read_b64_tr_b16 v[146:147], v249 offset:6144
	ds_read_b64_tr_b16 v[148:149], v249 offset:4608
	ds_read_b64_tr_b16 v[150:151], v249 offset:6656
	v_add_f32_e32 v250, v156, v250
	v_add_f32_e32 v250, v157, v250
	v_add_f32_e32 v250, v158, v250
	v_add_f32_e32 v250, v159, v250
	v_cvt_pk_bf16_f32 v234, v152, v153
	v_cvt_pk_bf16_f32 v235, v154, v155
	v_cvt_pk_bf16_f32 v236, v156, v157
	v_cvt_pk_bf16_f32 v237, v158, v159
	v_add_f32_e32 v219, v219, v250
	ds_read_b64_tr_b16 v[152:153], v249 offset:1024
	ds_read_b64_tr_b16 v[154:155], v249 offset:3072
	ds_read_b64_tr_b16 v[156:157], v249 offset:1536
	ds_read_b64_tr_b16 v[158:159], v249 offset:3584
	s_waitcnt lgkmcnt(8)
	v_mfma_f32_32x32x16_bf16 v[112:127], v[230:233], v[238:241], v[112:127]
	v_mfma_f32_32x32x16_bf16 v[96:111], v[230:233], v[242:245], v[96:111]
	ds_read_b64_tr_b16 v[238:239], v249 offset:5120
	ds_read_b64_tr_b16 v[240:241], v249 offset:7168
	ds_read_b64_tr_b16 v[242:243], v249 offset:5632
	ds_read_b64_tr_b16 v[244:245], v249 offset:7680
	s_add_i32 s30, s85, s34
	s_add_i32 m0, s30, 0x8000
	s_nop 0
	global_load_lds_dwordx4 v222, s[2:3] sc1
	s_waitcnt lgkmcnt(8)
	v_mfma_f32_32x32x16_bf16 v[112:127], v[234:237], v[144:147], v[112:127]
	v_mfma_f32_32x32x16_bf16 v[96:111], v[234:237], v[148:151], v[96:111]
	ds_read_b64_tr_b16 v[144:145], v249 offset:16384
	ds_read_b64_tr_b16 v[146:147], v249 offset:18432
	ds_read_b64_tr_b16 v[148:149], v249 offset:16896
	ds_read_b64_tr_b16 v[150:151], v249 offset:18944
	s_add_i32 s30, s85, s34
	s_add_i32 m0, s30, 0xa000
	s_nop 0
	global_load_lds_dwordx4 v221, s[2:3] sc1
	s_waitcnt lgkmcnt(8)
	v_mfma_f32_32x32x16_bf16 v[80:95], v[230:233], v[152:155], v[80:95]
	v_mfma_f32_32x32x16_bf16 v[64:79], v[230:233], v[156:159], v[64:79]
	ds_read_b64_tr_b16 v[152:153], v249 offset:20480
	ds_read_b64_tr_b16 v[154:155], v249 offset:22528
	ds_read_b64_tr_b16 v[156:157], v249 offset:20992
	ds_read_b64_tr_b16 v[158:159], v249 offset:23040
	s_add_i32 s30, s85, s34
	s_add_i32 m0, s30, 0xc000
	s_nop 0
	global_load_lds_dwordx4 v246, s[2:3] sc1
	s_waitcnt lgkmcnt(8)
	v_mfma_f32_32x32x16_bf16 v[80:95], v[234:237], v[238:241], v[80:95]
	v_mfma_f32_32x32x16_bf16 v[64:79], v[234:237], v[242:245], v[64:79]
	ds_read_b64_tr_b16 v[238:239], v249 offset:17408
	ds_read_b64_tr_b16 v[240:241], v249 offset:19456
	ds_read_b64_tr_b16 v[242:243], v249 offset:17920
	ds_read_b64_tr_b16 v[244:245], v249 offset:19968
	s_add_i32 s30, s85, s34
	s_add_i32 m0, s30, 0xe000
	s_nop 0
	global_load_lds_dwordx4 v247, s[2:3] sc1
	s_waitcnt lgkmcnt(8)
	v_mfma_f32_32x32x16_bf16 v[32:47], v[230:233], v[144:147], v[32:47]
	v_mfma_f32_32x32x16_bf16 v[16:31], v[230:233], v[148:151], v[16:31]
	ds_read_b64_tr_b16 v[144:145], v249 offset:21504
	ds_read_b64_tr_b16 v[146:147], v249 offset:23552
	ds_read_b64_tr_b16 v[148:149], v249 offset:22016
	ds_read_b64_tr_b16 v[150:151], v249 offset:24064
	s_waitcnt lgkmcnt(8)
	v_mfma_f32_32x32x16_bf16 v[32:47], v[234:237], v[152:155], v[32:47]
	v_mfma_f32_32x32x16_bf16 v[16:31], v[234:237], v[156:159], v[16:31]
	s_waitcnt lgkmcnt(0)
; #define SBAR() __builtin_amdgcn_sched_barrier(0)
; #define PVR(S, DA, DB, vbase) do { S[0] = tr_read<v_rd_off(DA, 0, 0)>(vbase); S[1] = tr_read<v_rd_off(DA, 0, 1)>(vbase); S[2] = tr_read<v_rd_off(DB, 0, 0)>(vbase); S[3] = tr_read<v_rd_off(DB, 0, 1)>(vbase); \
;     S[4] = tr_read<v_rd_off(DA, 1, 0)>(vbase); S[5] = tr_read<v_rd_off(DA, 1, 1)>(vbase); S[6] = tr_read<v_rd_off(DB, 1, 0)>(vbase); S[7] = tr_read<v_rd_off(DB, 1, 1)>(vbase); } while (0)
; #define RAWBAR() do { asm volatile("s_waitcnt lgkmcnt(0)" ::: "memory"); __builtin_amdgcn_s_barrier(); asm volatile("" ::: "memory"); } while (0)
; #define RAWBAR() do { asm volatile("s_waitcnt lgkmcnt(0)" ::: "memory"); __builtin_amdgcn_s_barrier(); asm volatile("" ::: "memory"); } while (0)
; #define RAWBAR() do { asm volatile("s_waitcnt lgkmcnt(0)" ::: "memory"); __builtin_amdgcn_s_barrier(); asm volatile("" ::: "memory"); } while (0)
; #define RAWBAR() do { asm volatile("s_waitcnt lgkmcnt(0)" ::: "memory"); __builtin_amdgcn_s_barrier(); asm volatile("" ::: "memory"); } while (0)
; #define RAWBAR() do { asm volatile("s_waitcnt lgkmcnt(0)" ::: "memory"); __builtin_amdgcn_s_barrier(); asm volatile("" ::: "memory"); } while (0)
; template <int MODE> ...
;     ...
;   for (int j = 0; j < NT; ++j) {
;     const int buf = j & 1;
;     if (j + 1 < NT) { STAGE((j + 1) * KVBLK, buf ^ 1); }
;     const char* Kb = K_lds + buf * 16384;
;     f32x16 pe = {}, po = {};
; #pragma unroll
;     for (int d0 = 0; d0 < 8; d0 += 2) {
;       const bf16x8 k0 = *reinterpret_cast<const bf16x8*>(Kb + KSWZ(krow, (d0 * 16 + hi * 8) * 2));
;       const bf16x8 k1 = *reinterpret_cast<const bf16x8*>(Kb + KSWZ(krow, ((d0 + 1) * 16 + hi * 8) * 2));
;       pe = __builtin_amdgcn_mfma_f32_32x32x16_bf16(k0, qr[d0], pe, 0, 0, 0);
;       po = __builtin_amdgcn_mfma_f32_32x32x16_bf16(k1, qr[d0 + 1], po, 0, 0, 0); }
;     const int vo = vb0 + buf * 32768;
;     s16x4 R0_[8], R1_[8];
;     PVR(R0_, 0, 1, vo);
;     f32x16 p;
; #pragma unroll
;     for (int r = 0; r < 16; ++r) p[r] = __builtin_amdgcn_exp2f(fmaf(pe[r] + po[r], C, negMc));
;     float ps = 0.f;
; #pragma unroll
;     for (int r = 0; r < 16; ++r) ps += p[r];
;     lsum += ps;
;     const bf16x8 own0 = pk8(p, 0), own1 = pk8(p, 8);
;     SBAR();
;     PV_TAIL4(o, vo, vo + 16384, own0, own1);
;     asm volatile("s_waitcnt vmcnt(0)" ::: "memory");
;     RAWBAR();
;   }
	v_mfma_f32_32x32x16_bf16 v[48:63], v[230:233], v[238:241], v[48:63]
	v_mfma_f32_32x32x16_bf16 v[0:15], v[230:233], v[242:245], v[0:15]
	v_mfma_f32_32x32x16_bf16 v[48:63], v[234:237], v[144:147], v[48:63]
	v_mfma_f32_32x32x16_bf16 v[0:15], v[234:237], v[148:151], v[0:15]
	s_add_i32 s84, s84, 0x8000
	s_cmp_eq_u32 s84, 0x18000
	s_cselect_b32 s84, 0, s84
	ds_read_b128 v[230:233], v229 offset:0
	ds_read_b128 v[234:237], v228 offset:0
	ds_read_b128 v[238:241], v227 offset:0
	ds_read_b128 v[242:245], v226 offset:0
	v_exp_f32_e32 v128, v128
	v_exp_f32_e32 v129, v129
	v_exp_f32_e32 v130, v130
	v_exp_f32_e32 v131, v131
	s_waitcnt lgkmcnt(2)
	v_mfma_f32_32x32x16_bf16 v[144:159], v[230:233], v[188:191], 0
	v_mfma_f32_32x32x16_bf16 v[144:159], v[234:237], v[184:187], v[144:159]
	ds_read_b128 v[230:233], v204 offset:0
	ds_read_b128 v[234:237], v205 offset:0
	v_exp_f32_e32 v132, v132
	v_exp_f32_e32 v133, v133
	v_exp_f32_e32 v134, v134
	v_exp_f32_e32 v135, v135
	v_add_f32_e32 v250, v128, v129
	v_add_f32_e32 v250, v130, v250
	v_add_f32_e32 v250, v131, v250
	s_waitcnt lgkmcnt(2)
	v_mfma_f32_32x32x16_bf16 v[144:159], v[238:241], v[180:183], v[144:159]
	v_mfma_f32_32x32x16_bf16 v[144:159], v[242:245], v[176:179], v[144:159]
	ds_read_b128 v[238:241], v206 offset:0
	ds_read_b128 v[242:245], v207 offset:0
	v_exp_f32_e32 v136, v136
	v_exp_f32_e32 v137, v137
	v_exp_f32_e32 v138, v138
	v_exp_f32_e32 v139, v139
	v_add_f32_e32 v250, v132, v250
	v_add_f32_e32 v250, v133, v250
	v_add_f32_e32 v250, v134, v250
	v_add_f32_e32 v250, v135, v250
	s_waitcnt lgkmcnt(2)
	v_mfma_f32_32x32x16_bf16 v[144:159], v[230:233], v[172:175], v[144:159]
	v_mfma_f32_32x32x16_bf16 v[144:159], v[234:237], v[168:171], v[144:159]
	v_exp_f32_e32 v140, v140
	v_exp_f32_e32 v141, v141
	v_exp_f32_e32 v142, v142
	v_exp_f32_e32 v143, v143
	v_add_f32_e32 v250, v136, v250
	v_add_f32_e32 v250, v137, v250
	v_add_f32_e32 v250, v138, v250
	v_add_f32_e32 v250, v139, v250
	v_cvt_pk_bf16_f32 v230, v128, v129
	v_cvt_pk_bf16_f32 v231, v130, v131
	v_cvt_pk_bf16_f32 v232, v132, v133
	v_cvt_pk_bf16_f32 v233, v134, v135
	s_waitcnt lgkmcnt(0)
	v_mfma_f32_32x32x16_bf16 v[144:159], v[238:241], v[164:167], v[144:159]
	v_mfma_f32_32x32x16_bf16 v[144:159], v[242:245], v[160:163], v[144:159]
	s_waitcnt vmcnt(0)
	s_barrier
	s_add_u32 s86, s86, 0x4000
	s_addc_u32 s87, s87, 0
	s_add_u32 s2, s2, 0x8000
	s_addc_u32 s3, s3, 0
	s_mov_b32 m0, s34
	s_nop 0
	global_load_lds_dwordx4 v225, s[86:87] sc1
	s_add_i32 m0, s34, 0x2000
	s_nop 0
	global_load_lds_dwordx4 v223, s[86:87] sc1
	v_add_u32_e32 v249, s84, v218
	s_sub_u32 s85, s84, 0x8000
	s_cmp_eq_u32 s84, 0
	s_cselect_b32 s85, 0x10000, s85
	ds_read_b64_tr_b16 v[238:239], v249 offset:0
	ds_read_b64_tr_b16 v[240:241], v249 offset:2048
	ds_read_b64_tr_b16 v[242:243], v249 offset:512
	ds_read_b64_tr_b16 v[244:245], v249 offset:2560
	ds_read_b64_tr_b16 v[128:129], v249 offset:4096
	ds_read_b64_tr_b16 v[130:131], v249 offset:6144
	ds_read_b64_tr_b16 v[132:133], v249 offset:4608
	ds_read_b64_tr_b16 v[134:135], v249 offset:6656
	v_add_f32_e32 v250, v140, v250
	v_add_f32_e32 v250, v141, v250
	v_add_f32_e32 v250, v142, v250
	v_add_f32_e32 v250, v143, v250
	v_cvt_pk_bf16_f32 v234, v136, v137
	v_cvt_pk_bf16_f32 v235, v138, v139
	v_cvt_pk_bf16_f32 v236, v140, v141
	v_cvt_pk_bf16_f32 v237, v142, v143
	v_add_f32_e32 v219, v219, v250
	ds_read_b64_tr_b16 v[136:137], v249 offset:1024
	ds_read_b64_tr_b16 v[138:139], v249 offset:3072
	ds_read_b64_tr_b16 v[140:141], v249 offset:1536
	ds_read_b64_tr_b16 v[142:143], v249 offset:3584
	s_waitcnt lgkmcnt(8)
	v_mfma_f32_32x32x16_bf16 v[112:127], v[230:233], v[238:241], v[112:127]
	v_mfma_f32_32x32x16_bf16 v[96:111], v[230:233], v[242:245], v[96:111]
	ds_read_b64_tr_b16 v[238:239], v249 offset:5120
	ds_read_b64_tr_b16 v[240:241], v249 offset:7168
	ds_read_b64_tr_b16 v[242:243], v249 offset:5632
	ds_read_b64_tr_b16 v[244:245], v249 offset:7680
	s_add_i32 s30, s85, s34
	s_add_i32 m0, s30, 0x8000
	s_nop 0
	global_load_lds_dwordx4 v222, s[2:3] sc1
	s_waitcnt lgkmcnt(8)
	v_mfma_f32_32x32x16_bf16 v[112:127], v[234:237], v[128:131], v[112:127]
	v_mfma_f32_32x32x16_bf16 v[96:111], v[234:237], v[132:135], v[96:111]
	ds_read_b64_tr_b16 v[128:129], v249 offset:16384
	ds_read_b64_tr_b16 v[130:131], v249 offset:18432
	ds_read_b64_tr_b16 v[132:133], v249 offset:16896
	ds_read_b64_tr_b16 v[134:135], v249 offset:18944
	s_add_i32 s30, s85, s34
	s_add_i32 m0, s30, 0xa000
	s_nop 0
	global_load_lds_dwordx4 v221, s[2:3] sc1
	s_waitcnt lgkmcnt(8)
	v_mfma_f32_32x32x16_bf16 v[80:95], v[230:233], v[136:139], v[80:95]
	v_mfma_f32_32x32x16_bf16 v[64:79], v[230:233], v[140:143], v[64:79]
	ds_read_b64_tr_b16 v[136:137], v249 offset:20480
	ds_read_b64_tr_b16 v[138:139], v249 offset:22528
	ds_read_b64_tr_b16 v[140:141], v249 offset:20992
	ds_read_b64_tr_b16 v[142:143], v249 offset:23040
	s_add_i32 s30, s85, s34
	s_add_i32 m0, s30, 0xc000
	s_nop 0
	global_load_lds_dwordx4 v246, s[2:3] sc1
	s_waitcnt lgkmcnt(8)
	v_mfma_f32_32x32x16_bf16 v[80:95], v[234:237], v[238:241], v[80:95]
	v_mfma_f32_32x32x16_bf16 v[64:79], v[234:237], v[242:245], v[64:79]
	ds_read_b64_tr_b16 v[238:239], v249 offset:17408
	ds_read_b64_tr_b16 v[240:241], v249 offset:19456
	ds_read_b64_tr_b16 v[242:243], v249 offset:17920
	ds_read_b64_tr_b16 v[244:245], v249 offset:19968
	s_add_i32 s30, s85, s34
	s_add_i32 m0, s30, 0xe000
	s_nop 0
	global_load_lds_dwordx4 v247, s[2:3] sc1
	s_waitcnt lgkmcnt(8)
	v_mfma_f32_32x32x16_bf16 v[32:47], v[230:233], v[128:131], v[32:47]
	v_mfma_f32_32x32x16_bf16 v[16:31], v[230:233], v[132:135], v[16:31]
	ds_read_b64_tr_b16 v[128:129], v249 offset:21504
	ds_read_b64_tr_b16 v[130:131], v249 offset:23552
	ds_read_b64_tr_b16 v[132:133], v249 offset:22016
	ds_read_b64_tr_b16 v[134:135], v249 offset:24064
	s_waitcnt lgkmcnt(8)
	v_mfma_f32_32x32x16_bf16 v[32:47], v[234:237], v[136:139], v[32:47]
	v_mfma_f32_32x32x16_bf16 v[16:31], v[234:237], v[140:143], v[16:31]
	s_waitcnt lgkmcnt(0)
	v_mfma_f32_32x32x16_bf16 v[48:63], v[230:233], v[238:241], v[48:63]
	v_mfma_f32_32x32x16_bf16 v[0:15], v[230:233], v[242:245], v[0:15]
	v_mfma_f32_32x32x16_bf16 v[48:63], v[234:237], v[128:131], v[48:63]
	v_mfma_f32_32x32x16_bf16 v[0:15], v[234:237], v[132:135], v[0:15]
	s_add_i32 s84, s84, 0x8000
	s_cmp_eq_u32 s84, 0x18000
	s_cselect_b32 s84, 0, s84
	s_add_i32 s40, s40, 1
	s_cmpk_eq_i32 s40, 0x82
	s_cbranch_scc0 .LattnB_m1
	s_waitcnt vmcnt(0)
	s_barrier
